# GEMM mainloops: 44 LDS-DMA loads use scalar base + 32-bit voffset (as the compiler's own prologue does), 24 64-bit address adds dropped
# speedup vs baseline: 1.0050x; 1.0050x over previous
; #define PG8_STAGE(bufoff, gbase, voff) do { _Pragma("unroll") for (int _i = 0; _i < 2; ++_i) \
;         __builtin_amdgcn_global_load_lds((const unsigned*)((const char*)(gbase) + (voff)[_i]), (LAS unsigned*)(lds + (bufoff) + ldsw + _i * 8192), 16, 0, 0); } while (0)
; #define PG8_LDA(dst, b, h) do { _Pragma("unroll") for (int m = 0; m < 4; ++m) _Pragma("unroll") for (int k = 0; k < 2; ++k) dst[m][k] = *(const LAS bf16x8*)(lds + PG8_SA(b, h) + aoff + m * 2048 + k * 1024); } while (0)
; #define PG8_LDB(dst, b, h) do { _Pragma("unroll") for (int n = 0; n < 2; ++n) _Pragma("unroll") for (int k = 0; k < 2; ++k) dst[n][k] = *(const LAS bf16x8*)(lds + PG8_SB(b, h) + boff + n * 2048 + k * 1024); } while (0)
; #define PG8_MMA(ai, bj, At, Bt) do { __builtin_amdgcn_s_setprio(1); _Pragma("unroll") for (int m = 0; m < 4; ++m) _Pragma("unroll") for (int n = 0; n < 2; ++n) _Pragma("unroll") for (int k = 0; k < 2; ++k) \
;         acc[ai][bj][m][n] = __builtin_amdgcn_mfma_f32_16x16x32_bf16(Bt[n][k], At[m][k], acc[ai][bj][m][n], 0, 0, 0); __builtin_amdgcn_s_setprio(0); } while (0)
; #define PG8_WAIT_V(n) asm volatile("s_waitcnt vmcnt(" #n ")" ::: "memory")
; #define PG8_WAIT_L(n) asm volatile("s_waitcnt lgkmcnt(" #n ")" ::: "memory")
; #define PG8_BAR __builtin_amdgcn_s_barrier()
; #define PG8_SCHED __builtin_amdgcn_sched_barrier(0)
; template <class Epi>
; __device__ __forceinline__ void gemm_phase(LAS unsigned char* lds, const Gemm g, const StaticOrder& S, const Epi& E, const int tid) {
;     ...
;         for (int t = 0; t < nt; t += 2) {
;             const bool last = (t == nt - 2);
;             const char* a1 = cA + (size_t)(t + 1) * kstep + ((t + 1) >= 8 ? xtra : 0);
;             const char* a2 = last ? nA : cA + (size_t)(t + 2) * kstep + ((t + 2) >= 8 ? xtra : 0); const char* b2 = last ? nB : cB + (size_t)(t + 2) * kstep;
;             const char* a3 = a2 + kstep; const char* b3 = b2 + kstep;
;             PG8_LDB(B0, 0, 0); PG8_LDB(B1, 0, 1); PG8_SCHED; PG8_LDA(At, 0, 0); PG8_STAGE(PG8_SA(1, 1), a1 + hstepA, voffA);
;             PG8_WAIT_V(8); PG8_WAIT_L(0); PG8_BAR; PG8_MMA(0, 0, At, B0); PG8_MMA(0, 1, At, B1); PG8_BAR; PG8_SCHED;
;             PG8_LDA(At, 0, 1); PG8_STAGE(PG8_SB(0, 0), b2, voffB); PG8_STAGE(PG8_SB(0, 1), b2 + hstepB, voffB); PG8_STAGE(PG8_SA(0, 0), a2, voffA);
.LBB0_160:
	s_add_u32 s42, s94, 0x100
	s_addc_u32 s43, s95, 0
	s_add_i32 s8, 0, 0x10000
	v_add_u32_e32 v142, s8, v245
	v_add_u32_e32 v158, s15, v245
	ds_read_b128 v[122:125], v142
	ds_read_b128 v[126:129], v142 offset:1024
	ds_read_b128 v[138:141], v142 offset:2048
	ds_read_b128 v[142:145], v142 offset:3072
	ds_read_b128 v[146:149], v158
	ds_read_b128 v[150:153], v158 offset:1024
	ds_read_b128 v[154:157], v158 offset:2048
	ds_read_b128 v[158:161], v158 offset:3072
	s_cmp_eq_u32 s89, 12
	s_cselect_b32 vcc_hi, s91, s43
	s_cselect_b32 vcc_lo, s90, s42
	s_cselect_b32 s93, s36, s46
	s_cselect_b32 s92, s37, s45
	v_lshl_add_u64 v[210:211], s[94:95], 0, v[206:207]
	s_add_i32 m0, s19, 0xc000
	ds_read_b128 v[162:165], v246
	ds_read_b128 v[166:169], v246 offset:1024
	ds_read_b128 v[170:173], v246 offset:2048
	ds_read_b128 v[174:177], v246 offset:3072
	ds_read_b128 v[178:181], v246 offset:4096
	ds_read_b128 v[182:185], v246 offset:5120
	ds_read_b128 v[186:189], v246 offset:6144
	ds_read_b128 v[190:193], v246 offset:7168
	global_load_lds_dwordx4 v[210:211], off
	v_lshl_add_u64 v[210:211], s[94:95], 0, v[208:209]
	s_add_i32 m0, s19, 0xe000
	s_nop 0
	global_load_lds_dwordx4 v[210:211], off
	s_waitcnt vmcnt(8)
	s_waitcnt lgkmcnt(0)
	s_barrier
	s_setprio 1
	s_waitcnt lgkmcnt(0)
	v_mfma_f32_16x16x32_bf16 v[134:137], v[122:125], v[162:165], v[134:137]
	v_mfma_f32_16x16x32_bf16 v[130:133], v[138:141], v[162:165], v[130:133]
	v_mfma_f32_16x16x32_bf16 v[108:111], v[122:125], v[170:173], v[108:111]
	v_mfma_f32_16x16x32_bf16 v[104:107], v[138:141], v[170:173], v[104:107]
	v_mfma_f32_16x16x32_bf16 v[92:95], v[122:125], v[178:181], v[92:95]
	v_mfma_f32_16x16x32_bf16 v[88:91], v[138:141], v[178:181], v[88:91]
	v_mfma_f32_16x16x32_bf16 v[76:79], v[122:125], v[186:189], v[76:79]
	v_mfma_f32_16x16x32_bf16 v[72:75], v[138:141], v[186:189], v[72:75]
	v_mfma_f32_16x16x32_bf16 v[134:137], v[126:129], v[166:169], v[134:137]
	v_mfma_f32_16x16x32_bf16 v[130:133], v[142:145], v[166:169], v[130:133]
	v_mfma_f32_16x16x32_bf16 v[108:111], v[126:129], v[174:177], v[108:111]
	v_mfma_f32_16x16x32_bf16 v[104:107], v[142:145], v[174:177], v[104:107]
	v_mfma_f32_16x16x32_bf16 v[92:95], v[126:129], v[182:185], v[92:95]
	v_mfma_f32_16x16x32_bf16 v[88:91], v[142:145], v[182:185], v[88:91]
	v_mfma_f32_16x16x32_bf16 v[76:79], v[126:129], v[190:193], v[76:79]
	v_mfma_f32_16x16x32_bf16 v[72:75], v[142:145], v[190:193], v[72:75]
	s_setprio 0
	s_setprio 1
	v_mfma_f32_16x16x32_bf16 v[118:121], v[146:149], v[162:165], v[118:121]
	v_mfma_f32_16x16x32_bf16 v[114:117], v[154:157], v[162:165], v[114:117]
	v_mfma_f32_16x16x32_bf16 v[100:103], v[146:149], v[170:173], v[100:103]
	v_mfma_f32_16x16x32_bf16 v[96:99], v[154:157], v[170:173], v[96:99]
	v_mfma_f32_16x16x32_bf16 v[84:87], v[146:149], v[178:181], v[84:87]
	v_mfma_f32_16x16x32_bf16 v[80:83], v[154:157], v[178:181], v[80:83]
	v_mfma_f32_16x16x32_bf16 v[68:71], v[146:149], v[186:189], v[68:71]
	v_mfma_f32_16x16x32_bf16 v[64:67], v[154:157], v[186:189], v[64:67]
	v_mfma_f32_16x16x32_bf16 v[118:121], v[150:153], v[166:169], v[118:121]
	v_mfma_f32_16x16x32_bf16 v[114:117], v[158:161], v[166:169], v[114:117]
	v_mfma_f32_16x16x32_bf16 v[100:103], v[150:153], v[174:177], v[100:103]
	v_mfma_f32_16x16x32_bf16 v[96:99], v[158:161], v[174:177], v[96:99]
	v_mfma_f32_16x16x32_bf16 v[84:87], v[150:153], v[182:185], v[84:87]
	v_mfma_f32_16x16x32_bf16 v[80:83], v[158:161], v[182:185], v[80:83]
	v_mfma_f32_16x16x32_bf16 v[68:71], v[150:153], v[190:193], v[68:71]
	v_mfma_f32_16x16x32_bf16 v[64:67], v[158:161], v[190:193], v[64:67]
	s_setprio 0
	s_barrier
	s_add_i32 s8, s8, s11
	v_lshl_add_u64 v[210:211], s[92:93], 0, v[112:113]
	s_mov_b32 m0, s8
	ds_read_b128 v[162:165], v246 offset:16384
	ds_read_b128 v[166:169], v246 offset:17408
	ds_read_b128 v[170:173], v246 offset:18432
	ds_read_b128 v[174:177], v246 offset:19456
	ds_read_b128 v[178:181], v246 offset:20480
	ds_read_b128 v[182:185], v246 offset:21504
	ds_read_b128 v[186:189], v246 offset:22528
	ds_read_b128 v[190:193], v246 offset:23552
	global_load_lds_dwordx4 v112, s[92:93]
	s_add_i32 m0, s8, 0x2000
	s_add_u32 s8, s92, 0x40000
	v_lshl_add_u64 v[212:213], s[92:93], 0, v[200:201]
	s_addc_u32 s9, s93, 0
	s_add_i32 s13, s15, s11
	global_load_lds_dwordx4 v200, s[92:93]
	s_nop 0
	s_mov_b32 m0, s13
	v_lshl_add_u64 v[228:229], vcc, 0, v[204:205]
	global_load_lds_dwordx4 v112, s[8:9]
	s_nop 0
	s_add_i32 m0, s13, 0x2000
	s_nop 0
	global_load_lds_dwordx4 v200, s[8:9]
	v_lshl_add_u64 v[214:215], vcc, 0, v[202:203]
	s_mov_b32 m0, s19
	s_nop 0
	global_load_lds_dwordx4 v202, vcc
	s_mov_b32 m0, s28
	s_nop 0
	global_load_lds_dwordx4 v204, vcc
	s_waitcnt vmcnt(8)
	s_waitcnt lgkmcnt(0)
	s_barrier
; #define PG8_STAGE(bufoff, gbase, voff) do { _Pragma("unroll") for (int _i = 0; _i < 2; ++_i) \
;         __builtin_amdgcn_global_load_lds((const unsigned*)((const char*)(gbase) + (voff)[_i]), (LAS unsigned*)(lds + (bufoff) + ldsw + _i * 8192), 16, 0, 0); } while (0)
; #define PG8_LDA(dst, b, h) do { _Pragma("unroll") for (int m = 0; m < 4; ++m) _Pragma("unroll") for (int k = 0; k < 2; ++k) dst[m][k] = *(const LAS bf16x8*)(lds + PG8_SA(b, h) + aoff + m * 2048 + k * 1024); } while (0)
; #define PG8_LDB(dst, b, h) do { _Pragma("unroll") for (int n = 0; n < 2; ++n) _Pragma("unroll") for (int k = 0; k < 2; ++k) dst[n][k] = *(const LAS bf16x8*)(lds + PG8_SB(b, h) + boff + n * 2048 + k * 1024); } while (0)
; #define PG8_MMA(ai, bj, At, Bt) do { __builtin_amdgcn_s_setprio(1); _Pragma("unroll") for (int m = 0; m < 4; ++m) _Pragma("unroll") for (int n = 0; n < 2; ++n) _Pragma("unroll") for (int k = 0; k < 2; ++k) \
;         acc[ai][bj][m][n] = __builtin_amdgcn_mfma_f32_16x16x32_bf16(Bt[n][k], At[m][k], acc[ai][bj][m][n], 0, 0, 0); __builtin_amdgcn_s_setprio(0); } while (0)
; #define PG8_WAIT_V(n) asm volatile("s_waitcnt vmcnt(" #n ")" ::: "memory")
; #define PG8_WAIT_L(n) asm volatile("s_waitcnt lgkmcnt(" #n ")" ::: "memory")
; #define PG8_BAR __builtin_amdgcn_s_barrier()
; #define PG8_SCHED __builtin_amdgcn_sched_barrier(0)
; template <class Epi>
; __device__ __forceinline__ void gemm_phase(LAS unsigned char* lds, const Gemm g, const StaticOrder& S, const Epi& E, const int tid) {
;     ...
;             PG8_LDA(At, 0, 1); PG8_STAGE(PG8_SB(0, 0), b2, voffB); PG8_STAGE(PG8_SB(0, 1), b2 + hstepB, voffB); PG8_STAGE(PG8_SA(0, 0), a2, voffA);
;             PG8_WAIT_V(8); PG8_WAIT_L(0); PG8_BAR; PG8_MMA(1, 0, At, B0); PG8_MMA(1, 1, At, B1); PG8_BAR; PG8_SCHED;
;             PG8_LDB(B0, 1, 0); PG8_LDB(B1, 1, 1); PG8_SCHED; PG8_LDA(At, 1, 0); PG8_STAGE(PG8_SA(0, 1), a2 + hstepA, voffA);
;             PG8_WAIT_V(8); PG8_WAIT_L(0); PG8_BAR; PG8_MMA(0, 0, At, B0); PG8_MMA(0, 1, At, B1); PG8_BAR; PG8_SCHED;
;             PG8_LDA(At, 1, 1); PG8_STAGE(PG8_SB(1, 0), b3, voffB); PG8_STAGE(PG8_SB(1, 1), b3 + hstepB, voffB); PG8_STAGE(PG8_SA(1, 0), a3, voffA);
	s_setprio 1
	s_waitcnt lgkmcnt(0)
	v_mfma_f32_16x16x32_bf16 v[60:63], v[122:125], v[162:165], v[60:63]
	v_mfma_f32_16x16x32_bf16 v[56:59], v[138:141], v[162:165], v[56:59]
	v_mfma_f32_16x16x32_bf16 v[44:47], v[122:125], v[170:173], v[44:47]
	v_mfma_f32_16x16x32_bf16 v[40:43], v[138:141], v[170:173], v[40:43]
	v_mfma_f32_16x16x32_bf16 v[28:31], v[122:125], v[178:181], v[28:31]
	v_mfma_f32_16x16x32_bf16 v[24:27], v[138:141], v[178:181], v[24:27]
	v_mfma_f32_16x16x32_bf16 v[12:15], v[122:125], v[186:189], v[12:15]
	v_mfma_f32_16x16x32_bf16 v[8:11], v[138:141], v[186:189], v[8:11]
	v_mfma_f32_16x16x32_bf16 v[60:63], v[126:129], v[166:169], v[60:63]
	v_mfma_f32_16x16x32_bf16 v[56:59], v[142:145], v[166:169], v[56:59]
	v_mfma_f32_16x16x32_bf16 v[44:47], v[126:129], v[174:177], v[44:47]
	v_mfma_f32_16x16x32_bf16 v[40:43], v[142:145], v[174:177], v[40:43]
	v_mfma_f32_16x16x32_bf16 v[28:31], v[126:129], v[182:185], v[28:31]
	v_mfma_f32_16x16x32_bf16 v[24:27], v[142:145], v[182:185], v[24:27]
	v_mfma_f32_16x16x32_bf16 v[12:15], v[126:129], v[190:193], v[12:15]
	v_mfma_f32_16x16x32_bf16 v[8:11], v[142:145], v[190:193], v[8:11]
	s_setprio 0
	s_setprio 1
	v_mfma_f32_16x16x32_bf16 v[52:55], v[146:149], v[162:165], v[52:55]
	v_mfma_f32_16x16x32_bf16 v[48:51], v[154:157], v[162:165], v[48:51]
	v_mfma_f32_16x16x32_bf16 v[36:39], v[146:149], v[170:173], v[36:39]
	v_mfma_f32_16x16x32_bf16 v[32:35], v[154:157], v[170:173], v[32:35]
	v_mfma_f32_16x16x32_bf16 v[20:23], v[146:149], v[178:181], v[20:23]
	v_mfma_f32_16x16x32_bf16 v[16:19], v[154:157], v[178:181], v[16:19]
	v_mfma_f32_16x16x32_bf16 v[4:7], v[146:149], v[186:189], v[4:7]
	v_mfma_f32_16x16x32_bf16 v[0:3], v[154:157], v[186:189], v[0:3]
	v_mfma_f32_16x16x32_bf16 v[52:55], v[150:153], v[166:169], v[52:55]
	v_mfma_f32_16x16x32_bf16 v[48:51], v[158:161], v[166:169], v[48:51]
	v_mfma_f32_16x16x32_bf16 v[36:39], v[150:153], v[174:177], v[36:39]
	v_mfma_f32_16x16x32_bf16 v[32:35], v[158:161], v[174:177], v[32:35]
	v_mfma_f32_16x16x32_bf16 v[20:23], v[150:153], v[182:185], v[20:23]
	v_mfma_f32_16x16x32_bf16 v[16:19], v[158:161], v[182:185], v[16:19]
	v_mfma_f32_16x16x32_bf16 v[4:7], v[150:153], v[190:193], v[4:7]
	v_mfma_f32_16x16x32_bf16 v[0:3], v[158:161], v[190:193], v[0:3]
	s_setprio 0
	s_barrier
	s_add_i32 s13, 0, 0x18000
	s_add_i32 s31, 0, 0x1c000
	v_add_u32_e32 v142, s13, v245
	v_add_u32_e32 v158, s31, v245
	ds_read_b128 v[122:125], v142
	ds_read_b128 v[126:129], v142 offset:1024
	ds_read_b128 v[138:141], v142 offset:2048
	ds_read_b128 v[142:145], v142 offset:3072
	ds_read_b128 v[146:149], v158
	ds_read_b128 v[150:153], v158 offset:1024
	ds_read_b128 v[154:157], v158 offset:2048
	ds_read_b128 v[158:161], v158 offset:3072
	s_add_u32 s8, vcc_lo, 0xc0000
	s_addc_u32 s9, vcc_hi, 0
	s_mov_b32 m0, s30
	s_nop 0
	ds_read_b128 v[162:165], v246 offset:32768
	ds_read_b128 v[166:169], v246 offset:33792
	ds_read_b128 v[170:173], v246 offset:34816
	ds_read_b128 v[174:177], v246 offset:35840
	ds_read_b128 v[178:181], v246 offset:36864
	ds_read_b128 v[182:185], v246 offset:37888
	ds_read_b128 v[186:189], v246 offset:38912
	ds_read_b128 v[190:193], v246 offset:39936
	global_load_lds_dwordx4 v202, s[8:9]
	v_lshl_add_u64 v[248:249], s[8:9], 0, v[204:205]
	s_mov_b32 m0, s35
	s_nop 0
	global_load_lds_dwordx4 v204, s[8:9]
	s_waitcnt vmcnt(8)
	s_waitcnt lgkmcnt(0)
	s_barrier
	s_setprio 1
	s_waitcnt lgkmcnt(0)
	v_mfma_f32_16x16x32_bf16 v[134:137], v[122:125], v[162:165], v[134:137]
	v_mfma_f32_16x16x32_bf16 v[130:133], v[138:141], v[162:165], v[130:133]
	v_mfma_f32_16x16x32_bf16 v[108:111], v[122:125], v[170:173], v[108:111]
	v_mfma_f32_16x16x32_bf16 v[104:107], v[138:141], v[170:173], v[104:107]
	v_mfma_f32_16x16x32_bf16 v[92:95], v[122:125], v[178:181], v[92:95]
	v_mfma_f32_16x16x32_bf16 v[88:91], v[138:141], v[178:181], v[88:91]
	v_mfma_f32_16x16x32_bf16 v[76:79], v[122:125], v[186:189], v[76:79]
	v_mfma_f32_16x16x32_bf16 v[72:75], v[138:141], v[186:189], v[72:75]
	v_mfma_f32_16x16x32_bf16 v[134:137], v[126:129], v[166:169], v[134:137]
	v_mfma_f32_16x16x32_bf16 v[130:133], v[142:145], v[166:169], v[130:133]
	v_mfma_f32_16x16x32_bf16 v[108:111], v[126:129], v[174:177], v[108:111]
	v_mfma_f32_16x16x32_bf16 v[104:107], v[142:145], v[174:177], v[104:107]
	v_mfma_f32_16x16x32_bf16 v[92:95], v[126:129], v[182:185], v[92:95]
	v_mfma_f32_16x16x32_bf16 v[88:91], v[142:145], v[182:185], v[88:91]
	v_mfma_f32_16x16x32_bf16 v[76:79], v[126:129], v[190:193], v[76:79]
	v_mfma_f32_16x16x32_bf16 v[72:75], v[142:145], v[190:193], v[72:75]
	s_setprio 0
	s_setprio 1
	v_mfma_f32_16x16x32_bf16 v[118:121], v[146:149], v[162:165], v[118:121]
	v_mfma_f32_16x16x32_bf16 v[114:117], v[154:157], v[162:165], v[114:117]
	v_mfma_f32_16x16x32_bf16 v[100:103], v[146:149], v[170:173], v[100:103]
	v_mfma_f32_16x16x32_bf16 v[96:99], v[154:157], v[170:173], v[96:99]
	v_mfma_f32_16x16x32_bf16 v[84:87], v[146:149], v[178:181], v[84:87]
	v_mfma_f32_16x16x32_bf16 v[80:83], v[154:157], v[178:181], v[80:83]
	v_mfma_f32_16x16x32_bf16 v[68:71], v[146:149], v[186:189], v[68:71]
	v_mfma_f32_16x16x32_bf16 v[64:67], v[154:157], v[186:189], v[64:67]
	v_mfma_f32_16x16x32_bf16 v[118:121], v[150:153], v[166:169], v[118:121]
	v_mfma_f32_16x16x32_bf16 v[114:117], v[158:161], v[166:169], v[114:117]
	v_mfma_f32_16x16x32_bf16 v[100:103], v[150:153], v[174:177], v[100:103]
	v_mfma_f32_16x16x32_bf16 v[96:99], v[158:161], v[174:177], v[96:99]
	v_mfma_f32_16x16x32_bf16 v[84:87], v[150:153], v[182:185], v[84:87]
	v_mfma_f32_16x16x32_bf16 v[80:83], v[158:161], v[182:185], v[80:83]
	v_mfma_f32_16x16x32_bf16 v[68:71], v[150:153], v[190:193], v[68:71]
	v_mfma_f32_16x16x32_bf16 v[64:67], v[158:161], v[190:193], v[64:67]
	s_setprio 0
	s_barrier
; #define PG8_STAGE(bufoff, gbase, voff) do { _Pragma("unroll") for (int _i = 0; _i < 2; ++_i) \
;         __builtin_amdgcn_global_load_lds((const unsigned*)((const char*)(gbase) + (voff)[_i]), (LAS unsigned*)(lds + (bufoff) + ldsw + _i * 8192), 16, 0, 0); } while (0)
; #define PG8_LDA(dst, b, h) do { _Pragma("unroll") for (int m = 0; m < 4; ++m) _Pragma("unroll") for (int k = 0; k < 2; ++k) dst[m][k] = *(const LAS bf16x8*)(lds + PG8_SA(b, h) + aoff + m * 2048 + k * 1024); } while (0)
; #define PG8_MMA(ai, bj, At, Bt) do { __builtin_amdgcn_s_setprio(1); _Pragma("unroll") for (int m = 0; m < 4; ++m) _Pragma("unroll") for (int n = 0; n < 2; ++n) _Pragma("unroll") for (int k = 0; k < 2; ++k) \
;         acc[ai][bj][m][n] = __builtin_amdgcn_mfma_f32_16x16x32_bf16(Bt[n][k], At[m][k], acc[ai][bj][m][n], 0, 0, 0); __builtin_amdgcn_s_setprio(0); } while (0)
; #define PG8_WAIT_V(n) asm volatile("s_waitcnt vmcnt(" #n ")" ::: "memory")
; #define PG8_WAIT_L(n) asm volatile("s_waitcnt lgkmcnt(" #n ")" ::: "memory")
; #define PG8_BAR __builtin_amdgcn_s_barrier()
; #define PG8_SCHED __builtin_amdgcn_sched_barrier(0)
; template <class Epi>
; __device__ __forceinline__ void gemm_phase(LAS unsigned char* lds, const Gemm g, const StaticOrder& S, const Epi& E, const int tid) {
;     ...
;             PG8_LDA(At, 1, 1); PG8_STAGE(PG8_SB(1, 0), b3, voffB); PG8_STAGE(PG8_SB(1, 1), b3 + hstepB, voffB); PG8_STAGE(PG8_SA(1, 0), a3, voffA);
;             PG8_WAIT_V(8); PG8_WAIT_L(0); PG8_BAR; PG8_MMA(1, 0, At, B0); PG8_MMA(1, 1, At, B1); PG8_BAR; PG8_SCHED;
;         }
	s_add_i32 s8, s13, s11
	v_lshl_add_u64 v[210:211], v[210:211], 0, s[24:25]
	s_mov_b32 m0, s8
	ds_read_b128 v[162:165], v246 offset:49152
	ds_read_b128 v[166:169], v246 offset:50176
	ds_read_b128 v[170:173], v246 offset:51200
	ds_read_b128 v[174:177], v246 offset:52224
	ds_read_b128 v[178:181], v246 offset:53248
	ds_read_b128 v[182:185], v246 offset:54272
	ds_read_b128 v[186:189], v246 offset:55296
	ds_read_b128 v[190:193], v246 offset:56320
	global_load_lds_dwordx4 v[210:211], off
	s_add_i32 m0, s8, 0x2000
	s_add_u32 s8, s92, 0x40080
	v_lshl_add_u64 v[210:211], v[212:213], 0, s[24:25]
	s_addc_u32 s9, s93, 0
	s_add_i32 s13, s31, s11
	global_load_lds_dwordx4 v[210:211], off
	s_nop 0
	s_mov_b32 m0, s13
	s_nop 0
	global_load_lds_dwordx4 v112, s[8:9]
	s_nop 0
	s_add_i32 m0, s13, 0x2000
	s_nop 0
	global_load_lds_dwordx4 v200, s[8:9]
	v_lshl_add_u64 v[210:211], v[214:215], 0, s[24:25]
	s_mov_b32 m0, s38
	s_nop 0
	global_load_lds_dwordx4 v[210:211], off
	v_lshl_add_u64 v[210:211], v[228:229], 0, s[24:25]
	s_mov_b32 m0, s39
	s_nop 0
	global_load_lds_dwordx4 v[210:211], off
	s_waitcnt vmcnt(8)
	s_waitcnt lgkmcnt(0)
	s_barrier
	s_setprio 1
	s_waitcnt lgkmcnt(0)
	v_mfma_f32_16x16x32_bf16 v[60:63], v[122:125], v[162:165], v[60:63]
	v_mfma_f32_16x16x32_bf16 v[56:59], v[138:141], v[162:165], v[56:59]
	v_mfma_f32_16x16x32_bf16 v[44:47], v[122:125], v[170:173], v[44:47]
	v_mfma_f32_16x16x32_bf16 v[40:43], v[138:141], v[170:173], v[40:43]
	v_mfma_f32_16x16x32_bf16 v[28:31], v[122:125], v[178:181], v[28:31]
	v_mfma_f32_16x16x32_bf16 v[24:27], v[138:141], v[178:181], v[24:27]
	v_mfma_f32_16x16x32_bf16 v[12:15], v[122:125], v[186:189], v[12:15]
	v_mfma_f32_16x16x32_bf16 v[8:11], v[138:141], v[186:189], v[8:11]
	v_mfma_f32_16x16x32_bf16 v[60:63], v[126:129], v[166:169], v[60:63]
	v_mfma_f32_16x16x32_bf16 v[56:59], v[142:145], v[166:169], v[56:59]
	v_mfma_f32_16x16x32_bf16 v[44:47], v[126:129], v[174:177], v[44:47]
	v_mfma_f32_16x16x32_bf16 v[40:43], v[142:145], v[174:177], v[40:43]
	v_mfma_f32_16x16x32_bf16 v[28:31], v[126:129], v[182:185], v[28:31]
	v_mfma_f32_16x16x32_bf16 v[24:27], v[142:145], v[182:185], v[24:27]
	v_mfma_f32_16x16x32_bf16 v[12:15], v[126:129], v[190:193], v[12:15]
	v_mfma_f32_16x16x32_bf16 v[8:11], v[142:145], v[190:193], v[8:11]
	s_setprio 0
	s_setprio 1
	v_mfma_f32_16x16x32_bf16 v[52:55], v[146:149], v[162:165], v[52:55]
	v_mfma_f32_16x16x32_bf16 v[48:51], v[154:157], v[162:165], v[48:51]
	v_mfma_f32_16x16x32_bf16 v[36:39], v[146:149], v[170:173], v[36:39]
	v_mfma_f32_16x16x32_bf16 v[32:35], v[154:157], v[170:173], v[32:35]
	v_mfma_f32_16x16x32_bf16 v[20:23], v[146:149], v[178:181], v[20:23]
	v_mfma_f32_16x16x32_bf16 v[16:19], v[154:157], v[178:181], v[16:19]
	v_mfma_f32_16x16x32_bf16 v[4:7], v[146:149], v[186:189], v[4:7]
	v_mfma_f32_16x16x32_bf16 v[0:3], v[154:157], v[186:189], v[0:3]
	v_mfma_f32_16x16x32_bf16 v[52:55], v[150:153], v[166:169], v[52:55]
	v_mfma_f32_16x16x32_bf16 v[48:51], v[158:161], v[166:169], v[48:51]
	v_mfma_f32_16x16x32_bf16 v[36:39], v[150:153], v[174:177], v[36:39]
	v_mfma_f32_16x16x32_bf16 v[32:35], v[158:161], v[174:177], v[32:35]
	v_mfma_f32_16x16x32_bf16 v[20:23], v[150:153], v[182:185], v[20:23]
	v_mfma_f32_16x16x32_bf16 v[16:19], v[158:161], v[182:185], v[16:19]
	v_mfma_f32_16x16x32_bf16 v[4:7], v[150:153], v[190:193], v[4:7]
	v_mfma_f32_16x16x32_bf16 v[0:3], v[158:161], v[190:193], v[0:3]
	s_setprio 0
	s_barrier
	s_add_i32 s89, s89, 2
	s_add_u32 s45, s45, 0x100
	s_addc_u32 s46, s46, 0
	s_cmp_gt_u32 s89, 13
	s_mov_b64 s[94:95], s[42:43]
	s_cbranch_scc0 .LBB0_160
	s_and_b64 vcc, exec, s[86:87]
	s_cbranch_vccz .LBB0_163
	s_barrier

; #define PG8_STAGE(bufoff, gbase, voff) do { _Pragma("unroll") for (int _i = 0; _i < 2; ++_i) \
;         __builtin_amdgcn_global_load_lds((const unsigned*)((const char*)(gbase) + (voff)[_i]), (LAS unsigned*)(lds + (bufoff) + ldsw + _i * 8192), 16, 0, 0); } while (0)
; #define PG8_LDA(dst, b, h) do { _Pragma("unroll") for (int m = 0; m < 4; ++m) _Pragma("unroll") for (int k = 0; k < 2; ++k) dst[m][k] = *(const LAS bf16x8*)(lds + PG8_SA(b, h) + aoff + m * 2048 + k * 1024); } while (0)
; #define PG8_LDB(dst, b, h) do { _Pragma("unroll") for (int n = 0; n < 2; ++n) _Pragma("unroll") for (int k = 0; k < 2; ++k) dst[n][k] = *(const LAS bf16x8*)(lds + PG8_SB(b, h) + boff + n * 2048 + k * 1024); } while (0)
; #define PG8_MMA(ai, bj, At, Bt) do { __builtin_amdgcn_s_setprio(1); _Pragma("unroll") for (int m = 0; m < 4; ++m) _Pragma("unroll") for (int n = 0; n < 2; ++n) _Pragma("unroll") for (int k = 0; k < 2; ++k) \
;         acc[ai][bj][m][n] = __builtin_amdgcn_mfma_f32_16x16x32_bf16(Bt[n][k], At[m][k], acc[ai][bj][m][n], 0, 0, 0); __builtin_amdgcn_s_setprio(0); } while (0)
; #define PG8_WAIT_V(n) asm volatile("s_waitcnt vmcnt(" #n ")" ::: "memory")
; #define PG8_WAIT_L(n) asm volatile("s_waitcnt lgkmcnt(" #n ")" ::: "memory")
; #define PG8_BAR __builtin_amdgcn_s_barrier()
; #define PG8_SCHED __builtin_amdgcn_sched_barrier(0)
; template <class Epi>
; __device__ __forceinline__ void gemm_phase(LAS unsigned char* lds, const Gemm g, const StaticOrder& S, const Epi& E, const int tid) {
;     ...
;         for (int t = 0; t < nt; t += 2) {
;             const bool last = (t == nt - 2);
;             const char* a1 = cA + (size_t)(t + 1) * kstep + ((t + 1) >= 8 ? xtra : 0);
;             const char* a2 = last ? nA : cA + (size_t)(t + 2) * kstep + ((t + 2) >= 8 ? xtra : 0); const char* b2 = last ? nB : cB + (size_t)(t + 2) * kstep;
;             const char* a3 = a2 + kstep; const char* b3 = b2 + kstep;
;             PG8_LDB(B0, 0, 0); PG8_LDB(B1, 0, 1); PG8_SCHED; PG8_LDA(At, 0, 0); PG8_STAGE(PG8_SA(1, 1), a1 + hstepA, voffA);
;             PG8_WAIT_V(8); PG8_WAIT_L(0); PG8_BAR; PG8_MMA(0, 0, At, B0); PG8_MMA(0, 1, At, B1); PG8_BAR; PG8_SCHED;
;             PG8_LDA(At, 0, 1); PG8_STAGE(PG8_SB(0, 0), b2, voffB); PG8_STAGE(PG8_SB(0, 1), b2 + hstepB, voffB); PG8_STAGE(PG8_SA(0, 0), a2, voffA);
.LBB0_230:
	s_add_i32 s96, s40, 2
	s_cmp_gt_u32 s96, 7
	s_cselect_b32 s46, 0x600, 0
	s_cmp_gt_u32 s96, 5
	s_cselect_b32 s8, 0x600, 0
	s_add_u32 s8, s88, s8
	s_addc_u32 s9, s89, 0
	s_add_u32 s8, s8, 0x100
	s_addc_u32 s9, s9, 0
	s_add_i32 s13, 0, 0x10000
	v_add_u32_e32 v142, s13, v210
	v_add_u32_e32 v158, s15, v210
	ds_read_b128 v[130:133], v142
	ds_read_b128 v[134:137], v142 offset:1024
	ds_read_b128 v[138:141], v142 offset:2048
	ds_read_b128 v[142:145], v142 offset:3072
	ds_read_b128 v[146:149], v158
	ds_read_b128 v[150:153], v158 offset:1024
	ds_read_b128 v[154:157], v158 offset:2048
	ds_read_b128 v[158:161], v158 offset:3072
	s_cmp_eq_u32 s40, 12
	s_cselect_b32 s40, s87, vcc_lo
	s_cselect_b32 s91, s83, s9
	s_cselect_b32 s90, s82, s8
	s_cselect_b32 s41, s81, vcc_hi
	v_lshl_add_u64 v[212:213], s[88:89], 0, v[190:191]
	v_lshl_add_u64 v[212:213], v[212:213], 0, s[46:47]
	s_add_i32 m0, s19, 0xc000
	ds_read_b128 v[162:165], v211
	ds_read_b128 v[166:169], v211 offset:1024
	ds_read_b128 v[170:173], v211 offset:2048
	ds_read_b128 v[174:177], v211 offset:3072
	ds_read_b128 v[178:181], v211 offset:4096
	ds_read_b128 v[182:185], v211 offset:5120
	ds_read_b128 v[202:205], v211 offset:6144
	ds_read_b128 v[206:209], v211 offset:7168
	global_load_lds_dwordx4 v[212:213], off
	v_lshl_add_u64 v[212:213], s[88:89], 0, v[192:193]
	v_lshl_add_u64 v[212:213], v[212:213], 0, s[46:47]
	s_add_i32 m0, s19, 0xe000
	s_nop 0
	global_load_lds_dwordx4 v[212:213], off
	s_waitcnt vmcnt(8)
	s_waitcnt lgkmcnt(0)
	s_barrier
	s_setprio 1
	s_waitcnt lgkmcnt(0)
	v_mfma_f32_16x16x32_bf16 v[126:129], v[130:133], v[162:165], v[126:129]
	v_mfma_f32_16x16x32_bf16 v[122:125], v[138:141], v[162:165], v[122:125]
	v_mfma_f32_16x16x32_bf16 v[108:111], v[130:133], v[170:173], v[108:111]
	v_mfma_f32_16x16x32_bf16 v[104:107], v[138:141], v[170:173], v[104:107]
	v_mfma_f32_16x16x32_bf16 v[92:95], v[130:133], v[178:181], v[92:95]
	v_mfma_f32_16x16x32_bf16 v[88:91], v[138:141], v[178:181], v[88:91]
	v_mfma_f32_16x16x32_bf16 v[76:79], v[130:133], v[202:205], v[76:79]
	v_mfma_f32_16x16x32_bf16 v[72:75], v[138:141], v[202:205], v[72:75]
	v_mfma_f32_16x16x32_bf16 v[126:129], v[134:137], v[166:169], v[126:129]
	v_mfma_f32_16x16x32_bf16 v[122:125], v[142:145], v[166:169], v[122:125]
	v_mfma_f32_16x16x32_bf16 v[108:111], v[134:137], v[174:177], v[108:111]
	v_mfma_f32_16x16x32_bf16 v[104:107], v[142:145], v[174:177], v[104:107]
	v_mfma_f32_16x16x32_bf16 v[92:95], v[134:137], v[182:185], v[92:95]
	v_mfma_f32_16x16x32_bf16 v[88:91], v[142:145], v[182:185], v[88:91]
	v_mfma_f32_16x16x32_bf16 v[76:79], v[134:137], v[206:209], v[76:79]
	v_mfma_f32_16x16x32_bf16 v[72:75], v[142:145], v[206:209], v[72:75]
	s_setprio 0
	s_setprio 1
	v_mfma_f32_16x16x32_bf16 v[118:121], v[146:149], v[162:165], v[118:121]
	v_mfma_f32_16x16x32_bf16 v[114:117], v[154:157], v[162:165], v[114:117]
	v_mfma_f32_16x16x32_bf16 v[100:103], v[146:149], v[170:173], v[100:103]
	v_mfma_f32_16x16x32_bf16 v[96:99], v[154:157], v[170:173], v[96:99]
	v_mfma_f32_16x16x32_bf16 v[84:87], v[146:149], v[178:181], v[84:87]
	v_mfma_f32_16x16x32_bf16 v[80:83], v[154:157], v[178:181], v[80:83]
	v_mfma_f32_16x16x32_bf16 v[68:71], v[146:149], v[202:205], v[68:71]
	v_mfma_f32_16x16x32_bf16 v[64:67], v[154:157], v[202:205], v[64:67]
	v_mfma_f32_16x16x32_bf16 v[118:121], v[150:153], v[166:169], v[118:121]
	v_mfma_f32_16x16x32_bf16 v[114:117], v[158:161], v[166:169], v[114:117]
	v_mfma_f32_16x16x32_bf16 v[100:103], v[150:153], v[174:177], v[100:103]
	v_mfma_f32_16x16x32_bf16 v[96:99], v[158:161], v[174:177], v[96:99]
	v_mfma_f32_16x16x32_bf16 v[84:87], v[150:153], v[182:185], v[84:87]
	v_mfma_f32_16x16x32_bf16 v[80:83], v[158:161], v[182:185], v[80:83]
	v_mfma_f32_16x16x32_bf16 v[68:71], v[150:153], v[206:209], v[68:71]
	v_mfma_f32_16x16x32_bf16 v[64:67], v[158:161], v[206:209], v[64:67]
	s_setprio 0
	s_barrier
	s_add_i32 s8, s13, s11
	v_lshl_add_u64 v[212:213], s[40:41], 0, v[112:113]
	s_mov_b32 m0, s8
	ds_read_b128 v[162:165], v211 offset:16384
	ds_read_b128 v[166:169], v211 offset:17408
	ds_read_b128 v[170:173], v211 offset:18432
	ds_read_b128 v[174:177], v211 offset:19456
	ds_read_b128 v[178:181], v211 offset:20480
	ds_read_b128 v[182:185], v211 offset:21504
	ds_read_b128 v[202:205], v211 offset:22528
	ds_read_b128 v[206:209], v211 offset:23552
	global_load_lds_dwordx4 v112, s[40:41]
	s_add_i32 m0, s8, 0x2000
	s_add_u32 s8, s40, 0x40000
	v_lshl_add_u64 v[214:215], s[40:41], 0, v[200:201]
	s_addc_u32 s9, s41, 0
	s_add_i32 s13, s15, s11
	global_load_lds_dwordx4 v200, s[40:41]
	s_nop 0
	s_mov_b32 m0, s13
	v_lshl_add_u64 v[236:237], s[90:91], 0, v[188:189]
	global_load_lds_dwordx4 v112, s[8:9]
	s_nop 0
	s_add_i32 m0, s13, 0x2000
	s_nop 0
	global_load_lds_dwordx4 v200, s[8:9]
	v_lshl_add_u64 v[228:229], s[90:91], 0, v[186:187]
	s_mov_b32 m0, s19
	s_nop 0
	global_load_lds_dwordx4 v186, s[90:91]
	s_mov_b32 m0, s23
	s_nop 0
	global_load_lds_dwordx4 v188, s[90:91]
	s_waitcnt vmcnt(8)
	s_waitcnt lgkmcnt(0)
	s_barrier
; #define PG8_STAGE(bufoff, gbase, voff) do { _Pragma("unroll") for (int _i = 0; _i < 2; ++_i) \
;         __builtin_amdgcn_global_load_lds((const unsigned*)((const char*)(gbase) + (voff)[_i]), (LAS unsigned*)(lds + (bufoff) + ldsw + _i * 8192), 16, 0, 0); } while (0)
; #define PG8_LDA(dst, b, h) do { _Pragma("unroll") for (int m = 0; m < 4; ++m) _Pragma("unroll") for (int k = 0; k < 2; ++k) dst[m][k] = *(const LAS bf16x8*)(lds + PG8_SA(b, h) + aoff + m * 2048 + k * 1024); } while (0)
; #define PG8_LDB(dst, b, h) do { _Pragma("unroll") for (int n = 0; n < 2; ++n) _Pragma("unroll") for (int k = 0; k < 2; ++k) dst[n][k] = *(const LAS bf16x8*)(lds + PG8_SB(b, h) + boff + n * 2048 + k * 1024); } while (0)
; #define PG8_MMA(ai, bj, At, Bt) do { __builtin_amdgcn_s_setprio(1); _Pragma("unroll") for (int m = 0; m < 4; ++m) _Pragma("unroll") for (int n = 0; n < 2; ++n) _Pragma("unroll") for (int k = 0; k < 2; ++k) \
;         acc[ai][bj][m][n] = __builtin_amdgcn_mfma_f32_16x16x32_bf16(Bt[n][k], At[m][k], acc[ai][bj][m][n], 0, 0, 0); __builtin_amdgcn_s_setprio(0); } while (0)
; #define PG8_WAIT_V(n) asm volatile("s_waitcnt vmcnt(" #n ")" ::: "memory")
; #define PG8_WAIT_L(n) asm volatile("s_waitcnt lgkmcnt(" #n ")" ::: "memory")
; #define PG8_BAR __builtin_amdgcn_s_barrier()
; #define PG8_SCHED __builtin_amdgcn_sched_barrier(0)
; template <class Epi>
; __device__ __forceinline__ void gemm_phase(LAS unsigned char* lds, const Gemm g, const StaticOrder& S, const Epi& E, const int tid) {
;     ...
;             PG8_LDA(At, 0, 1); PG8_STAGE(PG8_SB(0, 0), b2, voffB); PG8_STAGE(PG8_SB(0, 1), b2 + hstepB, voffB); PG8_STAGE(PG8_SA(0, 0), a2, voffA);
;             PG8_WAIT_V(8); PG8_WAIT_L(0); PG8_BAR; PG8_MMA(1, 0, At, B0); PG8_MMA(1, 1, At, B1); PG8_BAR; PG8_SCHED;
;             PG8_LDB(B0, 1, 0); PG8_LDB(B1, 1, 1); PG8_SCHED; PG8_LDA(At, 1, 0); PG8_STAGE(PG8_SA(0, 1), a2 + hstepA, voffA);
;             PG8_WAIT_V(8); PG8_WAIT_L(0); PG8_BAR; PG8_MMA(0, 0, At, B0); PG8_MMA(0, 1, At, B1); PG8_BAR; PG8_SCHED;
;             PG8_LDA(At, 1, 1); PG8_STAGE(PG8_SB(1, 0), b3, voffB); PG8_STAGE(PG8_SB(1, 1), b3 + hstepB, voffB); PG8_STAGE(PG8_SA(1, 0), a3, voffA);
	s_setprio 1
	s_waitcnt lgkmcnt(0)
	v_mfma_f32_16x16x32_bf16 v[60:63], v[130:133], v[162:165], v[60:63]
	v_mfma_f32_16x16x32_bf16 v[56:59], v[138:141], v[162:165], v[56:59]
	v_mfma_f32_16x16x32_bf16 v[44:47], v[130:133], v[170:173], v[44:47]
	v_mfma_f32_16x16x32_bf16 v[40:43], v[138:141], v[170:173], v[40:43]
	v_mfma_f32_16x16x32_bf16 v[28:31], v[130:133], v[178:181], v[28:31]
	v_mfma_f32_16x16x32_bf16 v[24:27], v[138:141], v[178:181], v[24:27]
	v_mfma_f32_16x16x32_bf16 v[12:15], v[130:133], v[202:205], v[12:15]
	v_mfma_f32_16x16x32_bf16 v[8:11], v[138:141], v[202:205], v[8:11]
	v_mfma_f32_16x16x32_bf16 v[60:63], v[134:137], v[166:169], v[60:63]
	v_mfma_f32_16x16x32_bf16 v[56:59], v[142:145], v[166:169], v[56:59]
	v_mfma_f32_16x16x32_bf16 v[44:47], v[134:137], v[174:177], v[44:47]
	v_mfma_f32_16x16x32_bf16 v[40:43], v[142:145], v[174:177], v[40:43]
	v_mfma_f32_16x16x32_bf16 v[28:31], v[134:137], v[182:185], v[28:31]
	v_mfma_f32_16x16x32_bf16 v[24:27], v[142:145], v[182:185], v[24:27]
	v_mfma_f32_16x16x32_bf16 v[12:15], v[134:137], v[206:209], v[12:15]
	v_mfma_f32_16x16x32_bf16 v[8:11], v[142:145], v[206:209], v[8:11]
	s_setprio 0
	s_setprio 1
	v_mfma_f32_16x16x32_bf16 v[52:55], v[146:149], v[162:165], v[52:55]
	v_mfma_f32_16x16x32_bf16 v[48:51], v[154:157], v[162:165], v[48:51]
	v_mfma_f32_16x16x32_bf16 v[36:39], v[146:149], v[170:173], v[36:39]
	v_mfma_f32_16x16x32_bf16 v[32:35], v[154:157], v[170:173], v[32:35]
	v_mfma_f32_16x16x32_bf16 v[20:23], v[146:149], v[178:181], v[20:23]
	v_mfma_f32_16x16x32_bf16 v[16:19], v[154:157], v[178:181], v[16:19]
	v_mfma_f32_16x16x32_bf16 v[4:7], v[146:149], v[202:205], v[4:7]
	v_mfma_f32_16x16x32_bf16 v[0:3], v[154:157], v[202:205], v[0:3]
	v_mfma_f32_16x16x32_bf16 v[52:55], v[150:153], v[166:169], v[52:55]
	v_mfma_f32_16x16x32_bf16 v[48:51], v[158:161], v[166:169], v[48:51]
	v_mfma_f32_16x16x32_bf16 v[36:39], v[150:153], v[174:177], v[36:39]
	v_mfma_f32_16x16x32_bf16 v[32:35], v[158:161], v[174:177], v[32:35]
	v_mfma_f32_16x16x32_bf16 v[20:23], v[150:153], v[182:185], v[20:23]
	v_mfma_f32_16x16x32_bf16 v[16:19], v[158:161], v[182:185], v[16:19]
	v_mfma_f32_16x16x32_bf16 v[4:7], v[150:153], v[206:209], v[4:7]
	v_mfma_f32_16x16x32_bf16 v[0:3], v[158:161], v[206:209], v[0:3]
	s_setprio 0
	s_barrier
	s_add_i32 s13, 0, 0x18000
	s_add_i32 s31, 0, 0x1c000
	v_add_u32_e32 v142, s13, v210
	v_add_u32_e32 v158, s31, v210
	ds_read_b128 v[130:133], v142
	ds_read_b128 v[134:137], v142 offset:1024
	ds_read_b128 v[138:141], v142 offset:2048
	ds_read_b128 v[142:145], v142 offset:3072
	ds_read_b128 v[146:149], v158
	ds_read_b128 v[150:153], v158 offset:1024
	ds_read_b128 v[154:157], v158 offset:2048
	ds_read_b128 v[158:161], v158 offset:3072
	s_add_u32 s8, s90, 0x90000
	s_addc_u32 s9, s91, 0
	s_mov_b32 m0, s28
	s_nop 0
	ds_read_b128 v[162:165], v211 offset:32768
	ds_read_b128 v[166:169], v211 offset:33792
	ds_read_b128 v[170:173], v211 offset:34816
	ds_read_b128 v[174:177], v211 offset:35840
	ds_read_b128 v[178:181], v211 offset:36864
	ds_read_b128 v[182:185], v211 offset:37888
	ds_read_b128 v[202:205], v211 offset:38912
	ds_read_b128 v[206:209], v211 offset:39936
	global_load_lds_dwordx4 v186, s[8:9]
	v_lshl_add_u64 v[238:239], s[8:9], 0, v[188:189]
	s_mov_b32 m0, s30
	s_nop 0
	global_load_lds_dwordx4 v188, s[8:9]
	s_waitcnt vmcnt(8)
	s_waitcnt lgkmcnt(0)
	s_barrier
	s_setprio 1
	s_waitcnt lgkmcnt(0)
	v_mfma_f32_16x16x32_bf16 v[126:129], v[130:133], v[162:165], v[126:129]
	v_mfma_f32_16x16x32_bf16 v[122:125], v[138:141], v[162:165], v[122:125]
	v_mfma_f32_16x16x32_bf16 v[108:111], v[130:133], v[170:173], v[108:111]
	v_mfma_f32_16x16x32_bf16 v[104:107], v[138:141], v[170:173], v[104:107]
	v_mfma_f32_16x16x32_bf16 v[92:95], v[130:133], v[178:181], v[92:95]
	v_mfma_f32_16x16x32_bf16 v[88:91], v[138:141], v[178:181], v[88:91]
	v_mfma_f32_16x16x32_bf16 v[76:79], v[130:133], v[202:205], v[76:79]
	v_mfma_f32_16x16x32_bf16 v[72:75], v[138:141], v[202:205], v[72:75]
	v_mfma_f32_16x16x32_bf16 v[126:129], v[134:137], v[166:169], v[126:129]
	v_mfma_f32_16x16x32_bf16 v[122:125], v[142:145], v[166:169], v[122:125]
	v_mfma_f32_16x16x32_bf16 v[108:111], v[134:137], v[174:177], v[108:111]
	v_mfma_f32_16x16x32_bf16 v[104:107], v[142:145], v[174:177], v[104:107]
	v_mfma_f32_16x16x32_bf16 v[92:95], v[134:137], v[182:185], v[92:95]
	v_mfma_f32_16x16x32_bf16 v[88:91], v[142:145], v[182:185], v[88:91]
	v_mfma_f32_16x16x32_bf16 v[76:79], v[134:137], v[206:209], v[76:79]
	v_mfma_f32_16x16x32_bf16 v[72:75], v[142:145], v[206:209], v[72:75]
	s_setprio 0
	s_setprio 1
	v_mfma_f32_16x16x32_bf16 v[118:121], v[146:149], v[162:165], v[118:121]
	v_mfma_f32_16x16x32_bf16 v[114:117], v[154:157], v[162:165], v[114:117]
	v_mfma_f32_16x16x32_bf16 v[100:103], v[146:149], v[170:173], v[100:103]
	v_mfma_f32_16x16x32_bf16 v[96:99], v[154:157], v[170:173], v[96:99]
	v_mfma_f32_16x16x32_bf16 v[84:87], v[146:149], v[178:181], v[84:87]
	v_mfma_f32_16x16x32_bf16 v[80:83], v[154:157], v[178:181], v[80:83]
	v_mfma_f32_16x16x32_bf16 v[68:71], v[146:149], v[202:205], v[68:71]
	v_mfma_f32_16x16x32_bf16 v[64:67], v[154:157], v[202:205], v[64:67]
	v_mfma_f32_16x16x32_bf16 v[118:121], v[150:153], v[166:169], v[118:121]
	v_mfma_f32_16x16x32_bf16 v[114:117], v[158:161], v[166:169], v[114:117]
	v_mfma_f32_16x16x32_bf16 v[100:103], v[150:153], v[174:177], v[100:103]
	v_mfma_f32_16x16x32_bf16 v[96:99], v[158:161], v[174:177], v[96:99]
	v_mfma_f32_16x16x32_bf16 v[84:87], v[150:153], v[182:185], v[84:87]
	v_mfma_f32_16x16x32_bf16 v[80:83], v[158:161], v[182:185], v[80:83]
	v_mfma_f32_16x16x32_bf16 v[68:71], v[150:153], v[206:209], v[68:71]
	v_mfma_f32_16x16x32_bf16 v[64:67], v[158:161], v[206:209], v[64:67]
	s_setprio 0
	s_barrier
; #define PG8_STAGE(bufoff, gbase, voff) do { _Pragma("unroll") for (int _i = 0; _i < 2; ++_i) \
;         __builtin_amdgcn_global_load_lds((const unsigned*)((const char*)(gbase) + (voff)[_i]), (LAS unsigned*)(lds + (bufoff) + ldsw + _i * 8192), 16, 0, 0); } while (0)
; #define PG8_LDA(dst, b, h) do { _Pragma("unroll") for (int m = 0; m < 4; ++m) _Pragma("unroll") for (int k = 0; k < 2; ++k) dst[m][k] = *(const LAS bf16x8*)(lds + PG8_SA(b, h) + aoff + m * 2048 + k * 1024); } while (0)
; #define PG8_MMA(ai, bj, At, Bt) do { __builtin_amdgcn_s_setprio(1); _Pragma("unroll") for (int m = 0; m < 4; ++m) _Pragma("unroll") for (int n = 0; n < 2; ++n) _Pragma("unroll") for (int k = 0; k < 2; ++k) \
;         acc[ai][bj][m][n] = __builtin_amdgcn_mfma_f32_16x16x32_bf16(Bt[n][k], At[m][k], acc[ai][bj][m][n], 0, 0, 0); __builtin_amdgcn_s_setprio(0); } while (0)
; #define PG8_WAIT_V(n) asm volatile("s_waitcnt vmcnt(" #n ")" ::: "memory")
; #define PG8_WAIT_L(n) asm volatile("s_waitcnt lgkmcnt(" #n ")" ::: "memory")
; #define PG8_BAR __builtin_amdgcn_s_barrier()
; #define PG8_SCHED __builtin_amdgcn_sched_barrier(0)
; template <class Epi>
; __device__ __forceinline__ void gemm_phase(LAS unsigned char* lds, const Gemm g, const StaticOrder& S, const Epi& E, const int tid) {
;     ...
;             PG8_LDA(At, 1, 1); PG8_STAGE(PG8_SB(1, 0), b3, voffB); PG8_STAGE(PG8_SB(1, 1), b3 + hstepB, voffB); PG8_STAGE(PG8_SA(1, 0), a3, voffA);
;             PG8_WAIT_V(8); PG8_WAIT_L(0); PG8_BAR; PG8_MMA(1, 0, At, B0); PG8_MMA(1, 1, At, B1); PG8_BAR; PG8_SCHED;
;         }
	s_add_i32 s8, s13, s11
	v_lshl_add_u64 v[212:213], v[212:213], 0, s[24:25]
	s_mov_b32 m0, s8
	ds_read_b128 v[162:165], v211 offset:49152
	ds_read_b128 v[166:169], v211 offset:50176
	ds_read_b128 v[170:173], v211 offset:51200
	ds_read_b128 v[174:177], v211 offset:52224
	ds_read_b128 v[178:181], v211 offset:53248
	ds_read_b128 v[182:185], v211 offset:54272
	ds_read_b128 v[202:205], v211 offset:55296
	ds_read_b128 v[206:209], v211 offset:56320
	global_load_lds_dwordx4 v[212:213], off
	s_add_i32 m0, s8, 0x2000
	s_add_u32 s8, s40, 0x40080
	v_lshl_add_u64 v[212:213], v[214:215], 0, s[24:25]
	s_addc_u32 s9, s41, 0
	s_add_i32 s13, s31, s11
	global_load_lds_dwordx4 v[212:213], off
	s_nop 0
	s_mov_b32 m0, s13
	s_nop 0
	global_load_lds_dwordx4 v112, s[8:9]
	s_nop 0
	s_add_i32 m0, s13, 0x2000
	s_nop 0
	global_load_lds_dwordx4 v200, s[8:9]
	v_lshl_add_u64 v[212:213], v[228:229], 0, s[24:25]
	s_mov_b32 m0, s99
	s_nop 0
	global_load_lds_dwordx4 v[212:213], off
	v_lshl_add_u64 v[212:213], v[236:237], 0, s[24:25]
	s_mov_b32 m0, s33
	s_nop 0
	global_load_lds_dwordx4 v[212:213], off
	s_waitcnt vmcnt(8)
	s_waitcnt lgkmcnt(0)
	s_barrier
	s_setprio 1
	s_waitcnt lgkmcnt(0)
	v_mfma_f32_16x16x32_bf16 v[60:63], v[130:133], v[162:165], v[60:63]
	v_mfma_f32_16x16x32_bf16 v[56:59], v[138:141], v[162:165], v[56:59]
	v_mfma_f32_16x16x32_bf16 v[44:47], v[130:133], v[170:173], v[44:47]
	v_mfma_f32_16x16x32_bf16 v[40:43], v[138:141], v[170:173], v[40:43]
	v_mfma_f32_16x16x32_bf16 v[28:31], v[130:133], v[178:181], v[28:31]
	v_mfma_f32_16x16x32_bf16 v[24:27], v[138:141], v[178:181], v[24:27]
	v_mfma_f32_16x16x32_bf16 v[12:15], v[130:133], v[202:205], v[12:15]
	v_mfma_f32_16x16x32_bf16 v[8:11], v[138:141], v[202:205], v[8:11]
	v_mfma_f32_16x16x32_bf16 v[60:63], v[134:137], v[166:169], v[60:63]
	v_mfma_f32_16x16x32_bf16 v[56:59], v[142:145], v[166:169], v[56:59]
	v_mfma_f32_16x16x32_bf16 v[44:47], v[134:137], v[174:177], v[44:47]
	v_mfma_f32_16x16x32_bf16 v[40:43], v[142:145], v[174:177], v[40:43]
	v_mfma_f32_16x16x32_bf16 v[28:31], v[134:137], v[182:185], v[28:31]
	v_mfma_f32_16x16x32_bf16 v[24:27], v[142:145], v[182:185], v[24:27]
	v_mfma_f32_16x16x32_bf16 v[12:15], v[134:137], v[206:209], v[12:15]
	v_mfma_f32_16x16x32_bf16 v[8:11], v[142:145], v[206:209], v[8:11]
	s_setprio 0
	s_setprio 1
	v_mfma_f32_16x16x32_bf16 v[52:55], v[146:149], v[162:165], v[52:55]
	v_mfma_f32_16x16x32_bf16 v[48:51], v[154:157], v[162:165], v[48:51]
	v_mfma_f32_16x16x32_bf16 v[36:39], v[146:149], v[170:173], v[36:39]
	v_mfma_f32_16x16x32_bf16 v[32:35], v[154:157], v[170:173], v[32:35]
	v_mfma_f32_16x16x32_bf16 v[20:23], v[146:149], v[178:181], v[20:23]
	v_mfma_f32_16x16x32_bf16 v[16:19], v[154:157], v[178:181], v[16:19]
	v_mfma_f32_16x16x32_bf16 v[4:7], v[146:149], v[202:205], v[4:7]
	v_mfma_f32_16x16x32_bf16 v[0:3], v[154:157], v[202:205], v[0:3]
	v_mfma_f32_16x16x32_bf16 v[52:55], v[150:153], v[166:169], v[52:55]
	v_mfma_f32_16x16x32_bf16 v[48:51], v[158:161], v[166:169], v[48:51]
	v_mfma_f32_16x16x32_bf16 v[36:39], v[150:153], v[174:177], v[36:39]
	v_mfma_f32_16x16x32_bf16 v[32:35], v[158:161], v[174:177], v[32:35]
	v_mfma_f32_16x16x32_bf16 v[20:23], v[150:153], v[182:185], v[20:23]
	v_mfma_f32_16x16x32_bf16 v[16:19], v[158:161], v[182:185], v[16:19]
	v_mfma_f32_16x16x32_bf16 v[4:7], v[150:153], v[206:209], v[4:7]
	v_mfma_f32_16x16x32_bf16 v[0:3], v[158:161], v[206:209], v[0:3]
	s_setprio 0
	s_barrier
	s_add_u32 s88, s88, 0x100
	s_addc_u32 s89, s89, 0
	s_add_u32 vcc_lo, vcc_lo, 0x100
	s_addc_u32 vcc_hi, vcc_hi, 0
	s_cmp_gt_u32 s96, 13
	s_mov_b32 s40, s96
	s_cbranch_scc0 .LBB0_230
	s_and_b64 vcc, exec, s[44:45]
	s_cbranch_vccz .LBB0_233
	s_barrier

; #define PG8_STAGE(bufoff, gbase, voff) do { _Pragma("unroll") for (int _i = 0; _i < 2; ++_i) \
;         __builtin_amdgcn_global_load_lds((const unsigned*)((const char*)(gbase) + (voff)[_i]), (LAS unsigned*)(lds + (bufoff) + ldsw + _i * 8192), 16, 0, 0); } while (0)
; #define PG8_LDA(dst, b, h) do { _Pragma("unroll") for (int m = 0; m < 4; ++m) _Pragma("unroll") for (int k = 0; k < 2; ++k) dst[m][k] = *(const LAS bf16x8*)(lds + PG8_SA(b, h) + aoff + m * 2048 + k * 1024); } while (0)
; #define PG8_LDB(dst, b, h) do { _Pragma("unroll") for (int n = 0; n < 2; ++n) _Pragma("unroll") for (int k = 0; k < 2; ++k) dst[n][k] = *(const LAS bf16x8*)(lds + PG8_SB(b, h) + boff + n * 2048 + k * 1024); } while (0)
; #define PG8_MMA(ai, bj, At, Bt) do { __builtin_amdgcn_s_setprio(1); _Pragma("unroll") for (int m = 0; m < 4; ++m) _Pragma("unroll") for (int n = 0; n < 2; ++n) _Pragma("unroll") for (int k = 0; k < 2; ++k) \
;         acc[ai][bj][m][n] = __builtin_amdgcn_mfma_f32_16x16x32_bf16(Bt[n][k], At[m][k], acc[ai][bj][m][n], 0, 0, 0); __builtin_amdgcn_s_setprio(0); } while (0)
; #define PG8_WAIT_V(n) asm volatile("s_waitcnt vmcnt(" #n ")" ::: "memory")
; #define PG8_WAIT_L(n) asm volatile("s_waitcnt lgkmcnt(" #n ")" ::: "memory")
; #define PG8_BAR __builtin_amdgcn_s_barrier()
; #define PG8_SCHED __builtin_amdgcn_sched_barrier(0)
; template <class Epi>
; __device__ __forceinline__ void gemm_phase(LAS unsigned char* lds, const Gemm g, const StaticOrder& S, const Epi& E, const int tid) {
;     ...
;         for (int t = 0; t < nt; t += 2) {
;             const bool last = (t == nt - 2);
;             const char* a1 = cA + (size_t)(t + 1) * kstep + ((t + 1) >= 8 ? xtra : 0);
;             const char* a2 = last ? nA : cA + (size_t)(t + 2) * kstep + ((t + 2) >= 8 ? xtra : 0); const char* b2 = last ? nB : cB + (size_t)(t + 2) * kstep;
;             const char* a3 = a2 + kstep; const char* b3 = b2 + kstep;
;             PG8_LDB(B0, 0, 0); PG8_LDB(B1, 0, 1); PG8_SCHED; PG8_LDA(At, 0, 0); PG8_STAGE(PG8_SA(1, 1), a1 + hstepA, voffA);
;             PG8_WAIT_V(8); PG8_WAIT_L(0); PG8_BAR; PG8_MMA(0, 0, At, B0); PG8_MMA(0, 1, At, B1); PG8_BAR; PG8_SCHED;
;             PG8_LDA(At, 0, 1); PG8_STAGE(PG8_SB(0, 0), b2, voffB); PG8_STAGE(PG8_SB(0, 1), b2 + hstepB, voffB); PG8_STAGE(PG8_SA(0, 0), a2, voffA);
.LBB0_268:
	s_add_u32 s8, s40, 0xfffc0080
	s_addc_u32 s9, s41, -1
	s_add_i32 s13, 0, 0x10000
	v_add_u32_e32 v162, s13, v167
	ds_read_b128 v[150:153], v162
	ds_read_b128 v[154:157], v162 offset:1024
	ds_read_b128 v[158:161], v162 offset:2048
	ds_read_b128 v[170:173], v162 offset:3072
	v_add_u32_e32 v162, s15, v167
	ds_read_b128 v[174:177], v162
	ds_read_b128 v[178:181], v162 offset:1024
	ds_read_b128 v[182:185], v162 offset:2048
	ds_read_b128 v[186:189], v162 offset:3072
	s_cmp_eq_u32 s85, 12
	s_cselect_b32 vcc_hi, s33, s9
	s_cselect_b32 vcc_lo, s36, s8
	s_cselect_b32 s95, s37, s57
	s_cselect_b32 s94, s45, s46
	s_nop 0
	s_add_i32 m0, s11, 0xc000
	ds_read_b128 v[190:193], v169
	ds_read_b128 v[200:203], v169 offset:1024
	ds_read_b128 v[204:207], v169 offset:2048
	ds_read_b128 v[208:211], v169 offset:3072
	ds_read_b128 v[212:215], v169 offset:4096
	ds_read_b128 v[234:237], v169 offset:5120
	ds_read_b128 v[238:241], v169 offset:6144
	ds_read_b128 v[242:245], v169 offset:7168
	global_load_lds_dwordx4 v146, s[40:41]
	s_nop 0
	s_add_i32 m0, s11, 0xe000
	s_nop 0
	global_load_lds_dwordx4 v148, s[40:41]
	s_waitcnt vmcnt(8)
	s_waitcnt lgkmcnt(0)
	s_barrier
	s_setprio 1
	s_waitcnt lgkmcnt(0)
	v_mfma_f32_16x16x32_bf16 v[134:137], v[150:153], v[190:193], v[134:137]
	v_mfma_f32_16x16x32_bf16 v[130:133], v[158:161], v[190:193], v[130:133]
	v_mfma_f32_16x16x32_bf16 v[118:121], v[150:153], v[204:207], v[118:121]
	v_mfma_f32_16x16x32_bf16 v[114:117], v[158:161], v[204:207], v[114:117]
	v_mfma_f32_16x16x32_bf16 v[100:103], v[150:153], v[212:215], v[100:103]
	v_mfma_f32_16x16x32_bf16 v[96:99], v[158:161], v[212:215], v[96:99]
	v_mfma_f32_16x16x32_bf16 v[84:87], v[150:153], v[238:241], v[84:87]
	v_mfma_f32_16x16x32_bf16 v[80:83], v[158:161], v[238:241], v[80:83]
	v_mfma_f32_16x16x32_bf16 v[134:137], v[154:157], v[200:203], v[134:137]
	v_mfma_f32_16x16x32_bf16 v[130:133], v[170:173], v[200:203], v[130:133]
	v_mfma_f32_16x16x32_bf16 v[118:121], v[154:157], v[208:211], v[118:121]
	v_mfma_f32_16x16x32_bf16 v[114:117], v[170:173], v[208:211], v[114:117]
	v_mfma_f32_16x16x32_bf16 v[100:103], v[154:157], v[234:237], v[100:103]
	v_mfma_f32_16x16x32_bf16 v[96:99], v[170:173], v[234:237], v[96:99]
	v_mfma_f32_16x16x32_bf16 v[84:87], v[154:157], v[242:245], v[84:87]
	v_mfma_f32_16x16x32_bf16 v[80:83], v[170:173], v[242:245], v[80:83]
	s_setprio 0
	s_setprio 1
	v_mfma_f32_16x16x32_bf16 v[126:129], v[174:177], v[190:193], v[126:129]
	v_mfma_f32_16x16x32_bf16 v[122:125], v[182:185], v[190:193], v[122:125]
	v_mfma_f32_16x16x32_bf16 v[108:111], v[174:177], v[204:207], v[108:111]
	v_mfma_f32_16x16x32_bf16 v[104:107], v[182:185], v[204:207], v[104:107]
	v_mfma_f32_16x16x32_bf16 v[92:95], v[174:177], v[212:215], v[92:95]
	v_mfma_f32_16x16x32_bf16 v[88:91], v[182:185], v[212:215], v[88:91]
	v_mfma_f32_16x16x32_bf16 v[76:79], v[174:177], v[238:241], v[76:79]
	v_mfma_f32_16x16x32_bf16 v[72:75], v[182:185], v[238:241], v[72:75]
	v_mfma_f32_16x16x32_bf16 v[126:129], v[178:181], v[200:203], v[126:129]
	v_mfma_f32_16x16x32_bf16 v[122:125], v[186:189], v[200:203], v[122:125]
	v_mfma_f32_16x16x32_bf16 v[108:111], v[178:181], v[208:211], v[108:111]
	v_mfma_f32_16x16x32_bf16 v[104:107], v[186:189], v[208:211], v[104:107]
	v_mfma_f32_16x16x32_bf16 v[92:95], v[178:181], v[234:237], v[92:95]
	v_mfma_f32_16x16x32_bf16 v[88:91], v[186:189], v[234:237], v[88:91]
	v_mfma_f32_16x16x32_bf16 v[76:79], v[178:181], v[242:245], v[76:79]
	v_mfma_f32_16x16x32_bf16 v[72:75], v[186:189], v[242:245], v[72:75]
	s_setprio 0
	s_barrier
	s_add_i32 s8, s13, s81
	v_lshl_add_u64 v[162:163], s[94:95], 0, v[112:113]
	s_mov_b32 m0, s8
	ds_read_b128 v[190:193], v169 offset:16384
	ds_read_b128 v[200:203], v169 offset:17408
	ds_read_b128 v[204:207], v169 offset:18432
	ds_read_b128 v[208:211], v169 offset:19456
	ds_read_b128 v[212:215], v169 offset:20480
	ds_read_b128 v[234:237], v169 offset:21504
	ds_read_b128 v[238:241], v169 offset:22528
	ds_read_b128 v[242:245], v169 offset:23552
	global_load_lds_dwordx4 v112, s[94:95]
	s_add_i32 m0, s8, 0x2000
	s_add_u32 s8, s94, 0x40000
	v_lshl_add_u64 v[228:229], s[94:95], 0, v[142:143]
	s_addc_u32 s9, s95, 0
	s_add_i32 s13, s15, s81
	global_load_lds_dwordx4 v142, s[94:95]
	s_nop 0
	s_mov_b32 m0, s13
	v_lshl_add_u64 v[248:249], vcc, 0, v[140:141]
	global_load_lds_dwordx4 v112, s[8:9]
	s_nop 0
	s_add_i32 m0, s13, 0x2000
	s_nop 0
	global_load_lds_dwordx4 v142, s[8:9]
	v_lshl_add_u64 v[246:247], vcc, 0, v[138:139]
	s_mov_b32 m0, s11
	s_nop 0
	global_load_lds_dwordx4 v138, vcc
	s_mov_b32 m0, s19
	s_nop 0
	global_load_lds_dwordx4 v140, vcc
	s_waitcnt vmcnt(8)
	s_waitcnt lgkmcnt(0)
	s_barrier
; #define PG8_STAGE(bufoff, gbase, voff) do { _Pragma("unroll") for (int _i = 0; _i < 2; ++_i) \
;         __builtin_amdgcn_global_load_lds((const unsigned*)((const char*)(gbase) + (voff)[_i]), (LAS unsigned*)(lds + (bufoff) + ldsw + _i * 8192), 16, 0, 0); } while (0)
; #define PG8_LDA(dst, b, h) do { _Pragma("unroll") for (int m = 0; m < 4; ++m) _Pragma("unroll") for (int k = 0; k < 2; ++k) dst[m][k] = *(const LAS bf16x8*)(lds + PG8_SA(b, h) + aoff + m * 2048 + k * 1024); } while (0)
; #define PG8_LDB(dst, b, h) do { _Pragma("unroll") for (int n = 0; n < 2; ++n) _Pragma("unroll") for (int k = 0; k < 2; ++k) dst[n][k] = *(const LAS bf16x8*)(lds + PG8_SB(b, h) + boff + n * 2048 + k * 1024); } while (0)
; #define PG8_MMA(ai, bj, At, Bt) do { __builtin_amdgcn_s_setprio(1); _Pragma("unroll") for (int m = 0; m < 4; ++m) _Pragma("unroll") for (int n = 0; n < 2; ++n) _Pragma("unroll") for (int k = 0; k < 2; ++k) \
;         acc[ai][bj][m][n] = __builtin_amdgcn_mfma_f32_16x16x32_bf16(Bt[n][k], At[m][k], acc[ai][bj][m][n], 0, 0, 0); __builtin_amdgcn_s_setprio(0); } while (0)
; #define PG8_WAIT_V(n) asm volatile("s_waitcnt vmcnt(" #n ")" ::: "memory")
; #define PG8_WAIT_L(n) asm volatile("s_waitcnt lgkmcnt(" #n ")" ::: "memory")
; #define PG8_BAR __builtin_amdgcn_s_barrier()
; #define PG8_SCHED __builtin_amdgcn_sched_barrier(0)
; template <class Epi>
; __device__ __forceinline__ void gemm_phase(LAS unsigned char* lds, const Gemm g, const StaticOrder& S, const Epi& E, const int tid) {
;     ...
;             PG8_LDA(At, 0, 1); PG8_STAGE(PG8_SB(0, 0), b2, voffB); PG8_STAGE(PG8_SB(0, 1), b2 + hstepB, voffB); PG8_STAGE(PG8_SA(0, 0), a2, voffA);
;             PG8_WAIT_V(8); PG8_WAIT_L(0); PG8_BAR; PG8_MMA(1, 0, At, B0); PG8_MMA(1, 1, At, B1); PG8_BAR; PG8_SCHED;
;             PG8_LDB(B0, 1, 0); PG8_LDB(B1, 1, 1); PG8_SCHED; PG8_LDA(At, 1, 0); PG8_STAGE(PG8_SA(0, 1), a2 + hstepA, voffA);
;             PG8_WAIT_V(8); PG8_WAIT_L(0); PG8_BAR; PG8_MMA(0, 0, At, B0); PG8_MMA(0, 1, At, B1); PG8_BAR; PG8_SCHED;
;             PG8_LDA(At, 1, 1); PG8_STAGE(PG8_SB(1, 0), b3, voffB); PG8_STAGE(PG8_SB(1, 1), b3 + hstepB, voffB); PG8_STAGE(PG8_SA(1, 0), a3, voffA);
	s_setprio 1
	s_waitcnt lgkmcnt(0)
	v_mfma_f32_16x16x32_bf16 v[68:71], v[150:153], v[190:193], v[68:71]
	v_mfma_f32_16x16x32_bf16 v[64:67], v[158:161], v[190:193], v[64:67]
	v_mfma_f32_16x16x32_bf16 v[52:55], v[150:153], v[204:207], v[52:55]
	v_mfma_f32_16x16x32_bf16 v[48:51], v[158:161], v[204:207], v[48:51]
	v_mfma_f32_16x16x32_bf16 v[36:39], v[150:153], v[212:215], v[36:39]
	v_mfma_f32_16x16x32_bf16 v[32:35], v[158:161], v[212:215], v[32:35]
	v_mfma_f32_16x16x32_bf16 v[20:23], v[150:153], v[238:241], v[20:23]
	v_mfma_f32_16x16x32_bf16 v[16:19], v[158:161], v[238:241], v[16:19]
	v_mfma_f32_16x16x32_bf16 v[68:71], v[154:157], v[200:203], v[68:71]
	v_mfma_f32_16x16x32_bf16 v[64:67], v[170:173], v[200:203], v[64:67]
	v_mfma_f32_16x16x32_bf16 v[52:55], v[154:157], v[208:211], v[52:55]
	v_mfma_f32_16x16x32_bf16 v[48:51], v[170:173], v[208:211], v[48:51]
	v_mfma_f32_16x16x32_bf16 v[36:39], v[154:157], v[234:237], v[36:39]
	v_mfma_f32_16x16x32_bf16 v[32:35], v[170:173], v[234:237], v[32:35]
	v_mfma_f32_16x16x32_bf16 v[20:23], v[154:157], v[242:245], v[20:23]
	v_mfma_f32_16x16x32_bf16 v[16:19], v[170:173], v[242:245], v[16:19]
	s_setprio 0
	s_setprio 1
	v_mfma_f32_16x16x32_bf16 v[60:63], v[174:177], v[190:193], v[60:63]
	v_mfma_f32_16x16x32_bf16 v[56:59], v[182:185], v[190:193], v[56:59]
	v_mfma_f32_16x16x32_bf16 v[44:47], v[174:177], v[204:207], v[44:47]
	v_mfma_f32_16x16x32_bf16 v[40:43], v[182:185], v[204:207], v[40:43]
	v_mfma_f32_16x16x32_bf16 v[28:31], v[174:177], v[212:215], v[28:31]
	v_mfma_f32_16x16x32_bf16 v[24:27], v[182:185], v[212:215], v[24:27]
	v_mfma_f32_16x16x32_bf16 v[12:15], v[174:177], v[238:241], v[12:15]
	v_mfma_f32_16x16x32_bf16 v[8:11], v[182:185], v[238:241], v[8:11]
	v_mfma_f32_16x16x32_bf16 v[60:63], v[178:181], v[200:203], v[60:63]
	v_mfma_f32_16x16x32_bf16 v[56:59], v[186:189], v[200:203], v[56:59]
	v_mfma_f32_16x16x32_bf16 v[44:47], v[178:181], v[208:211], v[44:47]
	v_mfma_f32_16x16x32_bf16 v[40:43], v[186:189], v[208:211], v[40:43]
	v_mfma_f32_16x16x32_bf16 v[28:31], v[178:181], v[234:237], v[28:31]
	v_mfma_f32_16x16x32_bf16 v[24:27], v[186:189], v[234:237], v[24:27]
	v_mfma_f32_16x16x32_bf16 v[12:15], v[178:181], v[242:245], v[12:15]
	v_mfma_f32_16x16x32_bf16 v[8:11], v[186:189], v[242:245], v[8:11]
	s_setprio 0
	s_barrier
	s_add_i32 s13, 0, 0x18000
	s_add_i32 s31, 0, 0x1c000
	v_add_u32_e32 v170, s13, v167
	v_add_u32_e32 v186, s31, v167
	ds_read_b128 v[150:153], v170
	ds_read_b128 v[154:157], v170 offset:1024
	ds_read_b128 v[158:161], v170 offset:2048
	ds_read_b128 v[170:173], v170 offset:3072
	ds_read_b128 v[174:177], v186
	ds_read_b128 v[178:181], v186 offset:1024
	ds_read_b128 v[182:185], v186 offset:2048
	ds_read_b128 v[186:189], v186 offset:3072
	s_add_u32 s8, vcc_lo, 0x40000
	s_addc_u32 s9, vcc_hi, 0
	s_mov_b32 m0, s98
	s_nop 0
	ds_read_b128 v[190:193], v169 offset:32768
	ds_read_b128 v[200:203], v169 offset:33792
	ds_read_b128 v[204:207], v169 offset:34816
	ds_read_b128 v[208:211], v169 offset:35840
	ds_read_b128 v[212:215], v169 offset:36864
	ds_read_b128 v[234:237], v169 offset:37888
	ds_read_b128 v[238:241], v169 offset:38912
	ds_read_b128 v[242:245], v169 offset:39936
	global_load_lds_dwordx4 v138, s[8:9]
	v_lshl_add_u64 v[250:251], s[8:9], 0, v[140:141]
	s_mov_b32 m0, s99
	s_nop 0
	global_load_lds_dwordx4 v140, s[8:9]
	s_waitcnt vmcnt(8)
	s_waitcnt lgkmcnt(0)
	s_barrier
	s_setprio 1
	s_waitcnt lgkmcnt(0)
	v_mfma_f32_16x16x32_bf16 v[134:137], v[150:153], v[190:193], v[134:137]
	v_mfma_f32_16x16x32_bf16 v[130:133], v[158:161], v[190:193], v[130:133]
	v_mfma_f32_16x16x32_bf16 v[118:121], v[150:153], v[204:207], v[118:121]
	v_mfma_f32_16x16x32_bf16 v[114:117], v[158:161], v[204:207], v[114:117]
	v_mfma_f32_16x16x32_bf16 v[100:103], v[150:153], v[212:215], v[100:103]
	v_mfma_f32_16x16x32_bf16 v[96:99], v[158:161], v[212:215], v[96:99]
	v_mfma_f32_16x16x32_bf16 v[84:87], v[150:153], v[238:241], v[84:87]
	v_mfma_f32_16x16x32_bf16 v[80:83], v[158:161], v[238:241], v[80:83]
	v_mfma_f32_16x16x32_bf16 v[134:137], v[154:157], v[200:203], v[134:137]
	v_mfma_f32_16x16x32_bf16 v[130:133], v[170:173], v[200:203], v[130:133]
	v_mfma_f32_16x16x32_bf16 v[118:121], v[154:157], v[208:211], v[118:121]
	v_mfma_f32_16x16x32_bf16 v[114:117], v[170:173], v[208:211], v[114:117]
	v_mfma_f32_16x16x32_bf16 v[100:103], v[154:157], v[234:237], v[100:103]
	v_mfma_f32_16x16x32_bf16 v[96:99], v[170:173], v[234:237], v[96:99]
	v_mfma_f32_16x16x32_bf16 v[84:87], v[154:157], v[242:245], v[84:87]
	v_mfma_f32_16x16x32_bf16 v[80:83], v[170:173], v[242:245], v[80:83]
	s_setprio 0
	s_setprio 1
	v_mfma_f32_16x16x32_bf16 v[126:129], v[174:177], v[190:193], v[126:129]
	v_mfma_f32_16x16x32_bf16 v[122:125], v[182:185], v[190:193], v[122:125]
	v_mfma_f32_16x16x32_bf16 v[108:111], v[174:177], v[204:207], v[108:111]
	v_mfma_f32_16x16x32_bf16 v[104:107], v[182:185], v[204:207], v[104:107]
	v_mfma_f32_16x16x32_bf16 v[92:95], v[174:177], v[212:215], v[92:95]
	v_mfma_f32_16x16x32_bf16 v[88:91], v[182:185], v[212:215], v[88:91]
	v_mfma_f32_16x16x32_bf16 v[76:79], v[174:177], v[238:241], v[76:79]
	v_mfma_f32_16x16x32_bf16 v[72:75], v[182:185], v[238:241], v[72:75]
	v_mfma_f32_16x16x32_bf16 v[126:129], v[178:181], v[200:203], v[126:129]
	v_mfma_f32_16x16x32_bf16 v[122:125], v[186:189], v[200:203], v[122:125]
	v_mfma_f32_16x16x32_bf16 v[108:111], v[178:181], v[208:211], v[108:111]
	v_mfma_f32_16x16x32_bf16 v[104:107], v[186:189], v[208:211], v[104:107]
	v_mfma_f32_16x16x32_bf16 v[92:95], v[178:181], v[234:237], v[92:95]
	v_mfma_f32_16x16x32_bf16 v[88:91], v[186:189], v[234:237], v[88:91]
	v_mfma_f32_16x16x32_bf16 v[76:79], v[178:181], v[242:245], v[76:79]
	v_mfma_f32_16x16x32_bf16 v[72:75], v[186:189], v[242:245], v[72:75]
	s_setprio 0
	s_barrier
; #define PG8_STAGE(bufoff, gbase, voff) do { _Pragma("unroll") for (int _i = 0; _i < 2; ++_i) \
;         __builtin_amdgcn_global_load_lds((const unsigned*)((const char*)(gbase) + (voff)[_i]), (LAS unsigned*)(lds + (bufoff) + ldsw + _i * 8192), 16, 0, 0); } while (0)
; #define PG8_LDA(dst, b, h) do { _Pragma("unroll") for (int m = 0; m < 4; ++m) _Pragma("unroll") for (int k = 0; k < 2; ++k) dst[m][k] = *(const LAS bf16x8*)(lds + PG8_SA(b, h) + aoff + m * 2048 + k * 1024); } while (0)
; #define PG8_MMA(ai, bj, At, Bt) do { __builtin_amdgcn_s_setprio(1); _Pragma("unroll") for (int m = 0; m < 4; ++m) _Pragma("unroll") for (int n = 0; n < 2; ++n) _Pragma("unroll") for (int k = 0; k < 2; ++k) \
;         acc[ai][bj][m][n] = __builtin_amdgcn_mfma_f32_16x16x32_bf16(Bt[n][k], At[m][k], acc[ai][bj][m][n], 0, 0, 0); __builtin_amdgcn_s_setprio(0); } while (0)
; #define PG8_WAIT_V(n) asm volatile("s_waitcnt vmcnt(" #n ")" ::: "memory")
; #define PG8_WAIT_L(n) asm volatile("s_waitcnt lgkmcnt(" #n ")" ::: "memory")
; #define PG8_BAR __builtin_amdgcn_s_barrier()
; #define PG8_SCHED __builtin_amdgcn_sched_barrier(0)
; template <class Epi>
; __device__ __forceinline__ void gemm_phase(LAS unsigned char* lds, const Gemm g, const StaticOrder& S, const Epi& E, const int tid) {
;     ...
;             PG8_LDA(At, 1, 1); PG8_STAGE(PG8_SB(1, 0), b3, voffB); PG8_STAGE(PG8_SB(1, 1), b3 + hstepB, voffB); PG8_STAGE(PG8_SA(1, 0), a3, voffA);
;             PG8_WAIT_V(8); PG8_WAIT_L(0); PG8_BAR; PG8_MMA(1, 0, At, B0); PG8_MMA(1, 1, At, B1); PG8_BAR; PG8_SCHED;
;         }
	s_add_i32 s8, s13, s81
	v_lshl_add_u64 v[162:163], v[162:163], 0, s[24:25]
	s_mov_b32 m0, s8
	ds_read_b128 v[190:193], v169 offset:49152
	ds_read_b128 v[200:203], v169 offset:50176
	ds_read_b128 v[204:207], v169 offset:51200
	ds_read_b128 v[208:211], v169 offset:52224
	ds_read_b128 v[212:215], v169 offset:53248
	ds_read_b128 v[234:237], v169 offset:54272
	ds_read_b128 v[238:241], v169 offset:55296
	ds_read_b128 v[242:245], v169 offset:56320
	global_load_lds_dwordx4 v[162:163], off
	s_add_i32 m0, s8, 0x2000
	s_add_u32 s8, s94, 0x40080
	v_lshl_add_u64 v[162:163], v[228:229], 0, s[24:25]
	s_addc_u32 s9, s95, 0
	s_add_i32 s13, s31, s81
	global_load_lds_dwordx4 v[162:163], off
	s_nop 0
	s_mov_b32 m0, s13
	s_nop 0
	global_load_lds_dwordx4 v112, s[8:9]
	s_nop 0
	s_add_i32 m0, s13, 0x2000
	s_nop 0
	global_load_lds_dwordx4 v142, s[8:9]
	v_lshl_add_u64 v[162:163], v[246:247], 0, s[24:25]
	s_mov_b32 m0, s38
	s_nop 0
	global_load_lds_dwordx4 v[162:163], off
	v_lshl_add_u64 v[162:163], v[248:249], 0, s[24:25]
	s_mov_b32 m0, s39
	s_nop 0
	global_load_lds_dwordx4 v[162:163], off
	s_waitcnt vmcnt(8)
	s_waitcnt lgkmcnt(0)
	s_barrier
	s_setprio 1
	s_waitcnt lgkmcnt(0)
	v_mfma_f32_16x16x32_bf16 v[68:71], v[150:153], v[190:193], v[68:71]
	v_mfma_f32_16x16x32_bf16 v[64:67], v[158:161], v[190:193], v[64:67]
	v_mfma_f32_16x16x32_bf16 v[52:55], v[150:153], v[204:207], v[52:55]
	v_mfma_f32_16x16x32_bf16 v[48:51], v[158:161], v[204:207], v[48:51]
	v_mfma_f32_16x16x32_bf16 v[36:39], v[150:153], v[212:215], v[36:39]
	v_mfma_f32_16x16x32_bf16 v[32:35], v[158:161], v[212:215], v[32:35]
	v_mfma_f32_16x16x32_bf16 v[20:23], v[150:153], v[238:241], v[20:23]
	v_mfma_f32_16x16x32_bf16 v[16:19], v[158:161], v[238:241], v[16:19]
	v_mfma_f32_16x16x32_bf16 v[68:71], v[154:157], v[200:203], v[68:71]
	v_mfma_f32_16x16x32_bf16 v[64:67], v[170:173], v[200:203], v[64:67]
	v_mfma_f32_16x16x32_bf16 v[52:55], v[154:157], v[208:211], v[52:55]
	v_mfma_f32_16x16x32_bf16 v[48:51], v[170:173], v[208:211], v[48:51]
	v_mfma_f32_16x16x32_bf16 v[36:39], v[154:157], v[234:237], v[36:39]
	v_mfma_f32_16x16x32_bf16 v[32:35], v[170:173], v[234:237], v[32:35]
	v_mfma_f32_16x16x32_bf16 v[20:23], v[154:157], v[242:245], v[20:23]
	v_mfma_f32_16x16x32_bf16 v[16:19], v[170:173], v[242:245], v[16:19]
	s_setprio 0
	s_setprio 1
	v_mfma_f32_16x16x32_bf16 v[60:63], v[174:177], v[190:193], v[60:63]
	v_mfma_f32_16x16x32_bf16 v[56:59], v[182:185], v[190:193], v[56:59]
	v_mfma_f32_16x16x32_bf16 v[44:47], v[174:177], v[204:207], v[44:47]
	v_mfma_f32_16x16x32_bf16 v[40:43], v[182:185], v[204:207], v[40:43]
	v_mfma_f32_16x16x32_bf16 v[28:31], v[174:177], v[212:215], v[28:31]
	v_mfma_f32_16x16x32_bf16 v[24:27], v[182:185], v[212:215], v[24:27]
	v_mfma_f32_16x16x32_bf16 v[12:15], v[174:177], v[238:241], v[12:15]
	v_mfma_f32_16x16x32_bf16 v[8:11], v[182:185], v[238:241], v[8:11]
	v_mfma_f32_16x16x32_bf16 v[60:63], v[178:181], v[200:203], v[60:63]
	v_mfma_f32_16x16x32_bf16 v[56:59], v[186:189], v[200:203], v[56:59]
	v_mfma_f32_16x16x32_bf16 v[44:47], v[178:181], v[208:211], v[44:47]
	v_mfma_f32_16x16x32_bf16 v[40:43], v[186:189], v[208:211], v[40:43]
	v_mfma_f32_16x16x32_bf16 v[28:31], v[178:181], v[234:237], v[28:31]
	v_mfma_f32_16x16x32_bf16 v[24:27], v[186:189], v[234:237], v[24:27]
	v_mfma_f32_16x16x32_bf16 v[12:15], v[178:181], v[242:245], v[12:15]
	v_mfma_f32_16x16x32_bf16 v[8:11], v[186:189], v[242:245], v[8:11]
	s_setprio 0
	s_barrier
	s_add_i32 s85, s85, 2
	s_add_u32 s40, s40, 0x100
	s_addc_u32 s41, s41, 0
	s_add_u32 s46, s46, 0x100
	s_addc_u32 s57, s57, 0
	s_cmp_gt_u32 s85, 13
	s_cbranch_scc0 .LBB0_268
	s_and_b64 vcc, exec, s[82:83]
	s_cbranch_vccz .LBB0_271
	s_barrier

; #define PG8_STAGE(bufoff, gbase, voff) do { _Pragma("unroll") for (int _i = 0; _i < 2; ++_i) \
;         __builtin_amdgcn_global_load_lds((const unsigned*)((const char*)(gbase) + (voff)[_i]), (LAS unsigned*)(lds + (bufoff) + ldsw + _i * 8192), 16, 0, 0); } while (0)
; #define PG8_LDA(dst, b, h) do { _Pragma("unroll") for (int m = 0; m < 4; ++m) _Pragma("unroll") for (int k = 0; k < 2; ++k) dst[m][k] = *(const LAS bf16x8*)(lds + PG8_SA(b, h) + aoff + m * 2048 + k * 1024); } while (0)
; #define PG8_LDB(dst, b, h) do { _Pragma("unroll") for (int n = 0; n < 2; ++n) _Pragma("unroll") for (int k = 0; k < 2; ++k) dst[n][k] = *(const LAS bf16x8*)(lds + PG8_SB(b, h) + boff + n * 2048 + k * 1024); } while (0)
; #define PG8_MMA(ai, bj, At, Bt) do { __builtin_amdgcn_s_setprio(1); _Pragma("unroll") for (int m = 0; m < 4; ++m) _Pragma("unroll") for (int n = 0; n < 2; ++n) _Pragma("unroll") for (int k = 0; k < 2; ++k) \
;         acc[ai][bj][m][n] = __builtin_amdgcn_mfma_f32_16x16x32_bf16(Bt[n][k], At[m][k], acc[ai][bj][m][n], 0, 0, 0); __builtin_amdgcn_s_setprio(0); } while (0)
; #define PG8_WAIT_V(n) asm volatile("s_waitcnt vmcnt(" #n ")" ::: "memory")
; #define PG8_WAIT_L(n) asm volatile("s_waitcnt lgkmcnt(" #n ")" ::: "memory")
; #define PG8_BAR __builtin_amdgcn_s_barrier()
; #define PG8_SCHED __builtin_amdgcn_sched_barrier(0)
; template <class Epi>
; __device__ __forceinline__ void gemm_phase(LAS unsigned char* lds, const Gemm g, const StaticOrder& S, const Epi& E, const int tid) {
;     ...
;         for (int t = 0; t < nt; t += 2) {
;             const bool last = (t == nt - 2);
;             const char* a1 = cA + (size_t)(t + 1) * kstep + ((t + 1) >= 8 ? xtra : 0);
;             const char* a2 = last ? nA : cA + (size_t)(t + 2) * kstep + ((t + 2) >= 8 ? xtra : 0); const char* b2 = last ? nB : cB + (size_t)(t + 2) * kstep;
;             const char* a3 = a2 + kstep; const char* b3 = b2 + kstep;
;             PG8_LDB(B0, 0, 0); PG8_LDB(B1, 0, 1); PG8_SCHED; PG8_LDA(At, 0, 0); PG8_STAGE(PG8_SA(1, 1), a1 + hstepA, voffA);
;             PG8_WAIT_V(8); PG8_WAIT_L(0); PG8_BAR; PG8_MMA(0, 0, At, B0); PG8_MMA(0, 1, At, B1); PG8_BAR; PG8_SCHED;
;             PG8_LDA(At, 0, 1); PG8_STAGE(PG8_SB(0, 0), b2, voffB); PG8_STAGE(PG8_SB(0, 1), b2 + hstepB, voffB); PG8_STAGE(PG8_SA(0, 0), a2, voffA);
.LBB0_356:
	s_add_u32 s8, s42, 0xfffc0080
	s_addc_u32 s9, s43, -1
	s_add_i32 s13, 0, 0x10000
	v_add_u32_e32 v168, s13, v161
	v_add_u32_e32 v184, s15, v161
	ds_read_b128 v[150:153], v168
	ds_read_b128 v[154:157], v168 offset:1024
	ds_read_b128 v[164:167], v168 offset:2048
	ds_read_b128 v[168:171], v168 offset:3072
	ds_read_b128 v[172:175], v184
	ds_read_b128 v[176:179], v184 offset:1024
	ds_read_b128 v[180:183], v184 offset:2048
	ds_read_b128 v[184:187], v184 offset:3072
	s_cmp_eq_u32 s97, 12
	s_cselect_b32 s95, s98, s9
	s_cselect_b32 s94, s99, s8
	s_cselect_b32 s93, s83, s96
	s_cselect_b32 s92, vcc_lo, vcc_hi
	s_nop 0
	s_add_i32 m0, s19, 0xc000
	ds_read_b128 v[188:191], v163
	ds_read_b128 v[200:203], v163 offset:1024
	ds_read_b128 v[204:207], v163 offset:2048
	ds_read_b128 v[208:211], v163 offset:3072
	ds_read_b128 v[212:215], v163 offset:4096
	ds_read_b128 v[234:237], v163 offset:5120
	ds_read_b128 v[238:241], v163 offset:6144
	ds_read_b128 v[242:245], v163 offset:7168
	global_load_lds_dwordx4 v146, s[42:43]
	s_nop 0
	s_add_i32 m0, s19, 0xe000
	s_nop 0
	global_load_lds_dwordx4 v148, s[42:43]
	s_waitcnt vmcnt(8)
	s_waitcnt lgkmcnt(0)
	s_barrier
	s_setprio 1
	s_waitcnt lgkmcnt(0)
	v_mfma_f32_16x16x32_bf16 v[134:137], v[150:153], v[188:191], v[134:137]
	v_mfma_f32_16x16x32_bf16 v[130:133], v[164:167], v[188:191], v[130:133]
	v_mfma_f32_16x16x32_bf16 v[122:125], v[150:153], v[204:207], v[122:125]
	v_mfma_f32_16x16x32_bf16 v[114:117], v[164:167], v[204:207], v[114:117]
	v_mfma_f32_16x16x32_bf16 v[104:107], v[150:153], v[212:215], v[104:107]
	v_mfma_f32_16x16x32_bf16 v[96:99], v[164:167], v[212:215], v[96:99]
	v_mfma_f32_16x16x32_bf16 v[88:91], v[150:153], v[238:241], v[88:91]
	v_mfma_f32_16x16x32_bf16 v[80:83], v[164:167], v[238:241], v[80:83]
	v_mfma_f32_16x16x32_bf16 v[134:137], v[154:157], v[200:203], v[134:137]
	v_mfma_f32_16x16x32_bf16 v[130:133], v[168:171], v[200:203], v[130:133]
	v_mfma_f32_16x16x32_bf16 v[122:125], v[154:157], v[208:211], v[122:125]
	v_mfma_f32_16x16x32_bf16 v[114:117], v[168:171], v[208:211], v[114:117]
	v_mfma_f32_16x16x32_bf16 v[104:107], v[154:157], v[234:237], v[104:107]
	v_mfma_f32_16x16x32_bf16 v[96:99], v[168:171], v[234:237], v[96:99]
	v_mfma_f32_16x16x32_bf16 v[88:91], v[154:157], v[242:245], v[88:91]
	v_mfma_f32_16x16x32_bf16 v[80:83], v[168:171], v[242:245], v[80:83]
	s_setprio 0
	s_setprio 1
	v_mfma_f32_16x16x32_bf16 v[126:129], v[172:175], v[188:191], v[126:129]
	v_mfma_f32_16x16x32_bf16 v[118:121], v[180:183], v[188:191], v[118:121]
	v_mfma_f32_16x16x32_bf16 v[108:111], v[172:175], v[204:207], v[108:111]
	v_mfma_f32_16x16x32_bf16 v[100:103], v[180:183], v[204:207], v[100:103]
	v_mfma_f32_16x16x32_bf16 v[92:95], v[172:175], v[212:215], v[92:95]
	v_mfma_f32_16x16x32_bf16 v[84:87], v[180:183], v[212:215], v[84:87]
	v_mfma_f32_16x16x32_bf16 v[76:79], v[172:175], v[238:241], v[76:79]
	v_mfma_f32_16x16x32_bf16 v[72:75], v[180:183], v[238:241], v[72:75]
	v_mfma_f32_16x16x32_bf16 v[126:129], v[176:179], v[200:203], v[126:129]
	v_mfma_f32_16x16x32_bf16 v[118:121], v[184:187], v[200:203], v[118:121]
	v_mfma_f32_16x16x32_bf16 v[108:111], v[176:179], v[208:211], v[108:111]
	v_mfma_f32_16x16x32_bf16 v[100:103], v[184:187], v[208:211], v[100:103]
	v_mfma_f32_16x16x32_bf16 v[92:95], v[176:179], v[234:237], v[92:95]
	v_mfma_f32_16x16x32_bf16 v[84:87], v[184:187], v[234:237], v[84:87]
	v_mfma_f32_16x16x32_bf16 v[76:79], v[176:179], v[242:245], v[76:79]
	v_mfma_f32_16x16x32_bf16 v[72:75], v[184:187], v[242:245], v[72:75]
	s_setprio 0
	s_barrier
	s_add_i32 s8, s13, s17
	v_lshl_add_u64 v[192:193], s[92:93], 0, v[112:113]
	s_mov_b32 m0, s8
	ds_read_b128 v[188:191], v163 offset:16384
	ds_read_b128 v[200:203], v163 offset:17408
	ds_read_b128 v[204:207], v163 offset:18432
	ds_read_b128 v[208:211], v163 offset:19456
	ds_read_b128 v[212:215], v163 offset:20480
	ds_read_b128 v[234:237], v163 offset:21504
	ds_read_b128 v[238:241], v163 offset:22528
	ds_read_b128 v[242:245], v163 offset:23552
	global_load_lds_dwordx4 v112, s[92:93]
	s_add_i32 m0, s8, 0x2000
	s_add_u32 s8, s92, 0x40000
	v_lshl_add_u64 v[246:247], s[92:93], 0, v[142:143]
	s_addc_u32 s9, s93, 0
	s_add_i32 s13, s15, s17
	global_load_lds_dwordx4 v142, s[92:93]
	s_nop 0
	s_mov_b32 m0, s13
	v_lshl_add_u64 v[250:251], s[94:95], 0, v[140:141]
	global_load_lds_dwordx4 v112, s[8:9]
	s_nop 0
	s_add_i32 m0, s13, 0x2000
	s_nop 0
	global_load_lds_dwordx4 v142, s[8:9]
	v_lshl_add_u64 v[248:249], s[94:95], 0, v[138:139]
	s_mov_b32 m0, s19
	s_nop 0
	global_load_lds_dwordx4 v138, s[94:95]
	s_mov_b32 m0, s23
	s_nop 0
	global_load_lds_dwordx4 v140, s[94:95]
	s_waitcnt vmcnt(8)
	s_waitcnt lgkmcnt(0)
	s_barrier
; #define PG8_STAGE(bufoff, gbase, voff) do { _Pragma("unroll") for (int _i = 0; _i < 2; ++_i) \
;         __builtin_amdgcn_global_load_lds((const unsigned*)((const char*)(gbase) + (voff)[_i]), (LAS unsigned*)(lds + (bufoff) + ldsw + _i * 8192), 16, 0, 0); } while (0)
; #define PG8_LDA(dst, b, h) do { _Pragma("unroll") for (int m = 0; m < 4; ++m) _Pragma("unroll") for (int k = 0; k < 2; ++k) dst[m][k] = *(const LAS bf16x8*)(lds + PG8_SA(b, h) + aoff + m * 2048 + k * 1024); } while (0)
; #define PG8_LDB(dst, b, h) do { _Pragma("unroll") for (int n = 0; n < 2; ++n) _Pragma("unroll") for (int k = 0; k < 2; ++k) dst[n][k] = *(const LAS bf16x8*)(lds + PG8_SB(b, h) + boff + n * 2048 + k * 1024); } while (0)
; #define PG8_MMA(ai, bj, At, Bt) do { __builtin_amdgcn_s_setprio(1); _Pragma("unroll") for (int m = 0; m < 4; ++m) _Pragma("unroll") for (int n = 0; n < 2; ++n) _Pragma("unroll") for (int k = 0; k < 2; ++k) \
;         acc[ai][bj][m][n] = __builtin_amdgcn_mfma_f32_16x16x32_bf16(Bt[n][k], At[m][k], acc[ai][bj][m][n], 0, 0, 0); __builtin_amdgcn_s_setprio(0); } while (0)
; #define PG8_WAIT_V(n) asm volatile("s_waitcnt vmcnt(" #n ")" ::: "memory")
; #define PG8_WAIT_L(n) asm volatile("s_waitcnt lgkmcnt(" #n ")" ::: "memory")
; #define PG8_BAR __builtin_amdgcn_s_barrier()
; #define PG8_SCHED __builtin_amdgcn_sched_barrier(0)
; template <class Epi>
; __device__ __forceinline__ void gemm_phase(LAS unsigned char* lds, const Gemm g, const StaticOrder& S, const Epi& E, const int tid) {
;     ...
;             PG8_LDA(At, 0, 1); PG8_STAGE(PG8_SB(0, 0), b2, voffB); PG8_STAGE(PG8_SB(0, 1), b2 + hstepB, voffB); PG8_STAGE(PG8_SA(0, 0), a2, voffA);
;             PG8_WAIT_V(8); PG8_WAIT_L(0); PG8_BAR; PG8_MMA(1, 0, At, B0); PG8_MMA(1, 1, At, B1); PG8_BAR; PG8_SCHED;
;             PG8_LDB(B0, 1, 0); PG8_LDB(B1, 1, 1); PG8_SCHED; PG8_LDA(At, 1, 0); PG8_STAGE(PG8_SA(0, 1), a2 + hstepA, voffA);
;             PG8_WAIT_V(8); PG8_WAIT_L(0); PG8_BAR; PG8_MMA(0, 0, At, B0); PG8_MMA(0, 1, At, B1); PG8_BAR; PG8_SCHED;
;             PG8_LDA(At, 1, 1); PG8_STAGE(PG8_SB(1, 0), b3, voffB); PG8_STAGE(PG8_SB(1, 1), b3 + hstepB, voffB); PG8_STAGE(PG8_SA(1, 0), a3, voffA);
	s_setprio 1
	s_waitcnt lgkmcnt(0)
	v_mfma_f32_16x16x32_bf16 v[68:71], v[150:153], v[188:191], v[68:71]
	v_mfma_f32_16x16x32_bf16 v[64:67], v[164:167], v[188:191], v[64:67]
	v_mfma_f32_16x16x32_bf16 v[56:59], v[150:153], v[204:207], v[56:59]
	v_mfma_f32_16x16x32_bf16 v[48:51], v[164:167], v[204:207], v[48:51]
	v_mfma_f32_16x16x32_bf16 v[40:43], v[150:153], v[212:215], v[40:43]
	v_mfma_f32_16x16x32_bf16 v[32:35], v[164:167], v[212:215], v[32:35]
	v_mfma_f32_16x16x32_bf16 v[24:27], v[150:153], v[238:241], v[24:27]
	v_mfma_f32_16x16x32_bf16 v[16:19], v[164:167], v[238:241], v[16:19]
	v_mfma_f32_16x16x32_bf16 v[68:71], v[154:157], v[200:203], v[68:71]
	v_mfma_f32_16x16x32_bf16 v[64:67], v[168:171], v[200:203], v[64:67]
	v_mfma_f32_16x16x32_bf16 v[56:59], v[154:157], v[208:211], v[56:59]
	v_mfma_f32_16x16x32_bf16 v[48:51], v[168:171], v[208:211], v[48:51]
	v_mfma_f32_16x16x32_bf16 v[40:43], v[154:157], v[234:237], v[40:43]
	v_mfma_f32_16x16x32_bf16 v[32:35], v[168:171], v[234:237], v[32:35]
	v_mfma_f32_16x16x32_bf16 v[24:27], v[154:157], v[242:245], v[24:27]
	v_mfma_f32_16x16x32_bf16 v[16:19], v[168:171], v[242:245], v[16:19]
	s_setprio 0
	s_setprio 1
	v_mfma_f32_16x16x32_bf16 v[60:63], v[172:175], v[188:191], v[60:63]
	v_mfma_f32_16x16x32_bf16 v[52:55], v[180:183], v[188:191], v[52:55]
	v_mfma_f32_16x16x32_bf16 v[44:47], v[172:175], v[204:207], v[44:47]
	v_mfma_f32_16x16x32_bf16 v[36:39], v[180:183], v[204:207], v[36:39]
	v_mfma_f32_16x16x32_bf16 v[28:31], v[172:175], v[212:215], v[28:31]
	v_mfma_f32_16x16x32_bf16 v[20:23], v[180:183], v[212:215], v[20:23]
	v_mfma_f32_16x16x32_bf16 v[12:15], v[172:175], v[238:241], v[12:15]
	v_mfma_f32_16x16x32_bf16 v[8:11], v[180:183], v[238:241], v[8:11]
	v_mfma_f32_16x16x32_bf16 v[60:63], v[176:179], v[200:203], v[60:63]
	v_mfma_f32_16x16x32_bf16 v[52:55], v[184:187], v[200:203], v[52:55]
	v_mfma_f32_16x16x32_bf16 v[44:47], v[176:179], v[208:211], v[44:47]
	v_mfma_f32_16x16x32_bf16 v[36:39], v[184:187], v[208:211], v[36:39]
	v_mfma_f32_16x16x32_bf16 v[28:31], v[176:179], v[234:237], v[28:31]
	v_mfma_f32_16x16x32_bf16 v[20:23], v[184:187], v[234:237], v[20:23]
	v_mfma_f32_16x16x32_bf16 v[12:15], v[176:179], v[242:245], v[12:15]
	v_mfma_f32_16x16x32_bf16 v[8:11], v[184:187], v[242:245], v[8:11]
	s_setprio 0
	s_barrier
	s_add_i32 s13, 0, 0x18000
	s_add_i32 s31, 0, 0x1c000
	v_add_u32_e32 v168, s13, v161
	v_add_u32_e32 v184, s31, v161
	ds_read_b128 v[150:153], v168
	ds_read_b128 v[154:157], v168 offset:1024
	ds_read_b128 v[164:167], v168 offset:2048
	ds_read_b128 v[168:171], v168 offset:3072
	ds_read_b128 v[172:175], v184
	ds_read_b128 v[176:179], v184 offset:1024
	ds_read_b128 v[180:183], v184 offset:2048
	ds_read_b128 v[184:187], v184 offset:3072
	s_add_u32 s8, s94, 0x40000
	s_addc_u32 s9, s95, 0
	s_mov_b32 m0, s28
	s_nop 0
	ds_read_b128 v[188:191], v163 offset:32768
	ds_read_b128 v[200:203], v163 offset:33792
	ds_read_b128 v[204:207], v163 offset:34816
	ds_read_b128 v[208:211], v163 offset:35840
	ds_read_b128 v[212:215], v163 offset:36864
	ds_read_b128 v[234:237], v163 offset:37888
	ds_read_b128 v[238:241], v163 offset:38912
	ds_read_b128 v[242:245], v163 offset:39936
	global_load_lds_dwordx4 v138, s[8:9]
	v_lshl_add_u64 v[228:229], s[8:9], 0, v[140:141]
	s_mov_b32 m0, s30
	s_nop 0
	global_load_lds_dwordx4 v140, s[8:9]
	s_waitcnt vmcnt(8)
	s_waitcnt lgkmcnt(0)
	s_barrier
	s_setprio 1
	s_waitcnt lgkmcnt(0)
	v_mfma_f32_16x16x32_bf16 v[134:137], v[150:153], v[188:191], v[134:137]
	v_mfma_f32_16x16x32_bf16 v[130:133], v[164:167], v[188:191], v[130:133]
	v_mfma_f32_16x16x32_bf16 v[122:125], v[150:153], v[204:207], v[122:125]
	v_mfma_f32_16x16x32_bf16 v[114:117], v[164:167], v[204:207], v[114:117]
	v_mfma_f32_16x16x32_bf16 v[104:107], v[150:153], v[212:215], v[104:107]
	v_mfma_f32_16x16x32_bf16 v[96:99], v[164:167], v[212:215], v[96:99]
	v_mfma_f32_16x16x32_bf16 v[88:91], v[150:153], v[238:241], v[88:91]
	v_mfma_f32_16x16x32_bf16 v[80:83], v[164:167], v[238:241], v[80:83]
	v_mfma_f32_16x16x32_bf16 v[134:137], v[154:157], v[200:203], v[134:137]
	v_mfma_f32_16x16x32_bf16 v[130:133], v[168:171], v[200:203], v[130:133]
	v_mfma_f32_16x16x32_bf16 v[122:125], v[154:157], v[208:211], v[122:125]
	v_mfma_f32_16x16x32_bf16 v[114:117], v[168:171], v[208:211], v[114:117]
	v_mfma_f32_16x16x32_bf16 v[104:107], v[154:157], v[234:237], v[104:107]
	v_mfma_f32_16x16x32_bf16 v[96:99], v[168:171], v[234:237], v[96:99]
	v_mfma_f32_16x16x32_bf16 v[88:91], v[154:157], v[242:245], v[88:91]
	v_mfma_f32_16x16x32_bf16 v[80:83], v[168:171], v[242:245], v[80:83]
	s_setprio 0
	s_setprio 1
	v_mfma_f32_16x16x32_bf16 v[126:129], v[172:175], v[188:191], v[126:129]
	v_mfma_f32_16x16x32_bf16 v[118:121], v[180:183], v[188:191], v[118:121]
	v_mfma_f32_16x16x32_bf16 v[108:111], v[172:175], v[204:207], v[108:111]
	v_mfma_f32_16x16x32_bf16 v[100:103], v[180:183], v[204:207], v[100:103]
	v_mfma_f32_16x16x32_bf16 v[92:95], v[172:175], v[212:215], v[92:95]
	v_mfma_f32_16x16x32_bf16 v[84:87], v[180:183], v[212:215], v[84:87]
	v_mfma_f32_16x16x32_bf16 v[76:79], v[172:175], v[238:241], v[76:79]
	v_mfma_f32_16x16x32_bf16 v[72:75], v[180:183], v[238:241], v[72:75]
	v_mfma_f32_16x16x32_bf16 v[126:129], v[176:179], v[200:203], v[126:129]
	v_mfma_f32_16x16x32_bf16 v[118:121], v[184:187], v[200:203], v[118:121]
	v_mfma_f32_16x16x32_bf16 v[108:111], v[176:179], v[208:211], v[108:111]
	v_mfma_f32_16x16x32_bf16 v[100:103], v[184:187], v[208:211], v[100:103]
	v_mfma_f32_16x16x32_bf16 v[92:95], v[176:179], v[234:237], v[92:95]
	v_mfma_f32_16x16x32_bf16 v[84:87], v[184:187], v[234:237], v[84:87]
	v_mfma_f32_16x16x32_bf16 v[76:79], v[176:179], v[242:245], v[76:79]
	v_mfma_f32_16x16x32_bf16 v[72:75], v[184:187], v[242:245], v[72:75]
	s_setprio 0
	s_barrier
; #define PG8_STAGE(bufoff, gbase, voff) do { _Pragma("unroll") for (int _i = 0; _i < 2; ++_i) \
;         __builtin_amdgcn_global_load_lds((const unsigned*)((const char*)(gbase) + (voff)[_i]), (LAS unsigned*)(lds + (bufoff) + ldsw + _i * 8192), 16, 0, 0); } while (0)
; #define PG8_LDA(dst, b, h) do { _Pragma("unroll") for (int m = 0; m < 4; ++m) _Pragma("unroll") for (int k = 0; k < 2; ++k) dst[m][k] = *(const LAS bf16x8*)(lds + PG8_SA(b, h) + aoff + m * 2048 + k * 1024); } while (0)
; #define PG8_MMA(ai, bj, At, Bt) do { __builtin_amdgcn_s_setprio(1); _Pragma("unroll") for (int m = 0; m < 4; ++m) _Pragma("unroll") for (int n = 0; n < 2; ++n) _Pragma("unroll") for (int k = 0; k < 2; ++k) \
;         acc[ai][bj][m][n] = __builtin_amdgcn_mfma_f32_16x16x32_bf16(Bt[n][k], At[m][k], acc[ai][bj][m][n], 0, 0, 0); __builtin_amdgcn_s_setprio(0); } while (0)
; #define PG8_WAIT_V(n) asm volatile("s_waitcnt vmcnt(" #n ")" ::: "memory")
; #define PG8_WAIT_L(n) asm volatile("s_waitcnt lgkmcnt(" #n ")" ::: "memory")
; #define PG8_BAR __builtin_amdgcn_s_barrier()
; #define PG8_SCHED __builtin_amdgcn_sched_barrier(0)
; template <class Epi>
; __device__ __forceinline__ void gemm_phase(LAS unsigned char* lds, const Gemm g, const StaticOrder& S, const Epi& E, const int tid) {
;     ...
;             PG8_LDA(At, 1, 1); PG8_STAGE(PG8_SB(1, 0), b3, voffB); PG8_STAGE(PG8_SB(1, 1), b3 + hstepB, voffB); PG8_STAGE(PG8_SA(1, 0), a3, voffA);
;             PG8_WAIT_V(8); PG8_WAIT_L(0); PG8_BAR; PG8_MMA(1, 0, At, B0); PG8_MMA(1, 1, At, B1); PG8_BAR; PG8_SCHED;
;         }
	s_add_i32 s8, s13, s17
	v_lshl_add_u64 v[192:193], v[192:193], 0, s[24:25]
	s_mov_b32 m0, s8
	ds_read_b128 v[188:191], v163 offset:49152
	ds_read_b128 v[200:203], v163 offset:50176
	ds_read_b128 v[204:207], v163 offset:51200
	ds_read_b128 v[208:211], v163 offset:52224
	ds_read_b128 v[212:215], v163 offset:53248
	ds_read_b128 v[234:237], v163 offset:54272
	ds_read_b128 v[238:241], v163 offset:55296
	ds_read_b128 v[242:245], v163 offset:56320
	global_load_lds_dwordx4 v[192:193], off
	s_add_i32 m0, s8, 0x2000
	s_add_u32 s8, s92, 0x40080
	v_lshl_add_u64 v[192:193], v[246:247], 0, s[24:25]
	s_addc_u32 s9, s93, 0
	s_add_i32 s13, s31, s17
	global_load_lds_dwordx4 v[192:193], off
	s_nop 0
	s_mov_b32 m0, s13
	s_nop 0
	global_load_lds_dwordx4 v112, s[8:9]
	s_nop 0
	s_add_i32 m0, s13, 0x2000
	s_nop 0
	global_load_lds_dwordx4 v142, s[8:9]
	v_lshl_add_u64 v[192:193], v[248:249], 0, s[24:25]
	s_mov_b32 m0, s36
	s_nop 0
	global_load_lds_dwordx4 v[192:193], off
	v_lshl_add_u64 v[192:193], v[250:251], 0, s[24:25]
	s_mov_b32 m0, s37
	s_nop 0
	global_load_lds_dwordx4 v[192:193], off
	s_waitcnt vmcnt(8)
	s_waitcnt lgkmcnt(0)
	s_barrier
	s_setprio 1
	s_waitcnt lgkmcnt(0)
	v_mfma_f32_16x16x32_bf16 v[68:71], v[150:153], v[188:191], v[68:71]
	v_mfma_f32_16x16x32_bf16 v[64:67], v[164:167], v[188:191], v[64:67]
	v_mfma_f32_16x16x32_bf16 v[56:59], v[150:153], v[204:207], v[56:59]
	v_mfma_f32_16x16x32_bf16 v[48:51], v[164:167], v[204:207], v[48:51]
	v_mfma_f32_16x16x32_bf16 v[40:43], v[150:153], v[212:215], v[40:43]
	v_mfma_f32_16x16x32_bf16 v[32:35], v[164:167], v[212:215], v[32:35]
	v_mfma_f32_16x16x32_bf16 v[24:27], v[150:153], v[238:241], v[24:27]
	v_mfma_f32_16x16x32_bf16 v[16:19], v[164:167], v[238:241], v[16:19]
	v_mfma_f32_16x16x32_bf16 v[68:71], v[154:157], v[200:203], v[68:71]
	v_mfma_f32_16x16x32_bf16 v[64:67], v[168:171], v[200:203], v[64:67]
	v_mfma_f32_16x16x32_bf16 v[56:59], v[154:157], v[208:211], v[56:59]
	v_mfma_f32_16x16x32_bf16 v[48:51], v[168:171], v[208:211], v[48:51]
	v_mfma_f32_16x16x32_bf16 v[40:43], v[154:157], v[234:237], v[40:43]
	v_mfma_f32_16x16x32_bf16 v[32:35], v[168:171], v[234:237], v[32:35]
	v_mfma_f32_16x16x32_bf16 v[24:27], v[154:157], v[242:245], v[24:27]
	v_mfma_f32_16x16x32_bf16 v[16:19], v[168:171], v[242:245], v[16:19]
	s_setprio 0
	s_setprio 1
	v_mfma_f32_16x16x32_bf16 v[60:63], v[172:175], v[188:191], v[60:63]
	v_mfma_f32_16x16x32_bf16 v[52:55], v[180:183], v[188:191], v[52:55]
	v_mfma_f32_16x16x32_bf16 v[44:47], v[172:175], v[204:207], v[44:47]
	v_mfma_f32_16x16x32_bf16 v[36:39], v[180:183], v[204:207], v[36:39]
	v_mfma_f32_16x16x32_bf16 v[28:31], v[172:175], v[212:215], v[28:31]
	v_mfma_f32_16x16x32_bf16 v[20:23], v[180:183], v[212:215], v[20:23]
	v_mfma_f32_16x16x32_bf16 v[12:15], v[172:175], v[238:241], v[12:15]
	v_mfma_f32_16x16x32_bf16 v[8:11], v[180:183], v[238:241], v[8:11]
	v_mfma_f32_16x16x32_bf16 v[60:63], v[176:179], v[200:203], v[60:63]
	v_mfma_f32_16x16x32_bf16 v[52:55], v[184:187], v[200:203], v[52:55]
	v_mfma_f32_16x16x32_bf16 v[44:47], v[176:179], v[208:211], v[44:47]
	v_mfma_f32_16x16x32_bf16 v[36:39], v[184:187], v[208:211], v[36:39]
	v_mfma_f32_16x16x32_bf16 v[28:31], v[176:179], v[234:237], v[28:31]
	v_mfma_f32_16x16x32_bf16 v[20:23], v[184:187], v[234:237], v[20:23]
	v_mfma_f32_16x16x32_bf16 v[12:15], v[176:179], v[242:245], v[12:15]
	v_mfma_f32_16x16x32_bf16 v[8:11], v[184:187], v[242:245], v[8:11]
	s_setprio 0
	s_barrier
	s_add_i32 s97, s97, 2
	s_add_u32 s42, s42, 0x100
	s_addc_u32 s43, s43, 0
	s_add_u32 vcc_hi, vcc_hi, 0x100
	s_addc_u32 s96, s96, 0
	s_cmp_gt_u32 s97, 13
	s_cbranch_scc0 .LBB0_356
	s_and_b64 vcc, exec, s[80:81]
	s_cbranch_vccz .LBB0_359
	s_barrier
